# attention: K tiles staged row-major with XOR swizzle so each wave's LDS-DMA fetches whole 128-B rows (8x fewer L2 requests per K line)
# baseline (speedup 1.0000x reference)
; #define LAS __attribute__((address_space(3)))
; __device__ __forceinline__ void attn_unit(LAS unsigned char* lds, bf16_t* P, const float* qgain, const float* rope, int s, int h, int qb, int lane, int wid, bool dry) {
;     ...
;     *(LAS u32x4*)(lds + kdst) = krA; *(LAS u32x4*)(lds + vdst) = vrA; *(LAS u32x4*)(lds + 8192 + kdst) = krB;
;     asm volatile("s_waitcnt vmcnt(0) lgkmcnt(0)\n\ts_barrier" ::: "memory");
;     krA = *(const u32x4*)(ksrc + (size_t)2 * 64 * EVEN_IN); vrA = *(const u32x4*)(vsrc + (size_t)64 * EVEN_IN);
;     const int koff = hi * 1024 + r32 * 16;
;     const int voff = 16384 + ((lane >> 4) & 1) * 32 + (lane & 3) * 8 + (4 * hi + ((lane & 15) >> 2)) * 64;
.Lfa_g0_entry:
	v_lshl_add_u64 v[146:147], v[174:175], 0, s[46:47]
	v_lshl_add_u64 v[148:149], v[172:173], 0, s[46:47]
	s_nop 0
	v_readfirstlane_b32 s84, v146
	v_readfirstlane_b32 s85, v147
	v_readfirstlane_b32 s82, v148
	v_readfirstlane_b32 s83, v149
	s_nop 3
	v_subrev_u32_e32 v174, s84, v146
	v_subrev_u32_e32 v172, s82, v148
	s_add_u32 s84, s84, 0x88d8c00
	s_addc_u32 s85, s85, 0
	s_add_u32 s82, s82, 0x8890d00
	s_addc_u32 s83, s83, 0
	s_nop 4
	s_lshl_b32 s40, s38, 10
	s_lshr_b32 s41, s38, 2
	s_lshl_b32 s41, s41, 12
	s_and_b32 s39, s38, 3
	s_lshl_b32 s39, s39, 10
	s_add_i32 s41, s41, s39
	s_add_i32 s41, s41, 16384
	s_waitcnt vmcnt(0)
	s_lshl_b32 s39, s38, 4
	s_sub_u32 s84, s84, s39
	s_subb_u32 s85, s85, 0
	v_lshrrev_b32_e32 v142, 3, v198
	v_lshl_add_u32 v142, s38, 3, v142
	v_bfe_u32 v143, v142, 1, 3
	v_and_b32_e32 v144, 7, v198
	v_xor_b32_e32 v143, v143, v144
	v_mul_u32_u24_e32 v174, 0x1200, v142
	v_lshl_add_u32 v174, v143, 4, v174
	v_and_b32_e32 v142, 31, v198
	v_lshrrev_b32_e32 v143, 5, v198
	v_bfe_u32 v144, v142, 1, 3
	v_lshlrev_b32_e32 v142, 7, v142
	v_or_b32_e32 v145, 0, v143
	v_xor_b32_e32 v145, v145, v144
	v_lshl_add_u32 v114, v145, 4, v142
	v_or_b32_e32 v145, 2, v143
	v_xor_b32_e32 v145, v145, v144
	v_lshl_add_u32 v115, v145, 4, v142
	v_or_b32_e32 v145, 4, v143
	v_xor_b32_e32 v145, v145, v144
	v_lshl_add_u32 v116, v145, 4, v142
	v_or_b32_e32 v145, 6, v143
	v_xor_b32_e32 v145, v145, v144
	v_lshl_add_u32 v117, v145, 4, v142
	s_sub_u32 s22, s84, 0x90000
	s_subb_u32 s23, s85, 0
	s_add_i32 m0, s40, 8192
	s_nop 0
	global_load_lds_dwordx4 v174, s[22:23]
	s_add_u32 s22, s22, 0x48000
	s_addc_u32 s23, s23, 0
	s_add_i32 m0, s40, 49152
	s_nop 0
	global_load_lds_dwordx4 v174, s[22:23]
	ds_write_b128 v178, v[138:141] offset:24576
	s_waitcnt vmcnt(0) lgkmcnt(0)
	s_barrier
	s_mov_b32 s80, 0
.Lfa_g0_loop:
	s_add_i32 m0, s40, 57344
	s_nop 0
	global_load_lds_dwordx4 v174, s[84:85]
	s_add_i32 m0, s41, 16384
	s_nop 0
	global_load_lds_dwordx4 v172, s[82:83]
	s_add_u32 s84, s84, 0x48000
	s_addc_u32 s85, s85, 0
	s_add_u32 s82, s82, 0x48000
	s_addc_u32 s83, s83, 0
	ds_read_b128 v[80:83], v114 offset:8192
	ds_read_b128 v[182:185], v114 offset:12288
	ds_read_b128 v[186:189], v115 offset:8192
	ds_read_b128 v[190:193], v115 offset:12288
	ds_read_b128 v[200:203], v116 offset:8192
	ds_read_b128 v[204:207], v116 offset:12288
	ds_read_b128 v[208:211], v117 offset:8192
	ds_read_b128 v[212:215], v117 offset:12288
	v_exp_f32_e32 v64, v64
	v_exp_f32_e32 v65, v65
	v_exp_f32_e32 v66, v66
	v_exp_f32_e32 v67, v67
	v_exp_f32_e32 v48, v48
	v_exp_f32_e32 v49, v49
	v_exp_f32_e32 v50, v50
	v_exp_f32_e32 v51, v51
	v_add_f32_e32 v84, v50, v66
	v_add_f32_e32 v85, v51, v67
	v_add_f32_e32 v86, v48, v64
	v_add_f32_e32 v87, v49, v65
	v_cvt_pk_bf16_f32 v64, v64, v65
	v_cvt_pk_bf16_f32 v65, v66, v67
	v_cvt_pk_bf16_f32 v48, v48, v49
	v_cvt_pk_bf16_f32 v49, v50, v51
	s_waitcnt lgkmcnt(7)
	v_mfma_f32_32x32x16_bf16 v[96:111], v[80:83], v[118:121], v[32:47]
	v_exp_f32_e32 v50, v68
	v_exp_f32_e32 v51, v69
	v_exp_f32_e32 v68, v70
	v_exp_f32_e32 v69, v71
	v_add_f32_e32 v70, v50, v86
	v_add_f32_e32 v71, v51, v87
	v_add_f32_e32 v181, v68, v84
	v_add_f32_e32 v228, v69, v85
	v_cvt_pk_bf16_f32 v66, v50, v51
	v_cvt_pk_bf16_f32 v67, v68, v69
	s_waitcnt lgkmcnt(6)
	v_mfma_f32_32x32x16_bf16 v[80:95], v[182:185], v[118:121], v[32:47]
	v_exp_f32_e32 v50, v52
	v_exp_f32_e32 v51, v53
	v_exp_f32_e32 v52, v54
	v_exp_f32_e32 v53, v55
	v_add_f32_e32 v54, v50, v70
	v_add_f32_e32 v55, v51, v71
	v_add_f32_e32 v68, v52, v181
	v_add_f32_e32 v69, v53, v228
	v_cvt_pk_bf16_f32 v50, v50, v51
	v_cvt_pk_bf16_f32 v51, v52, v53
	s_waitcnt lgkmcnt(5)
	v_mfma_f32_32x32x16_bf16 v[96:111], v[186:189], v[122:125], v[96:111]
	v_exp_f32_e32 v52, v72
	v_exp_f32_e32 v53, v73
	v_exp_f32_e32 v70, v74
	v_exp_f32_e32 v71, v75
	v_add_f32_e32 v54, v52, v54
	v_add_f32_e32 v55, v53, v55
	v_add_f32_e32 v72, v70, v68
	v_add_f32_e32 v73, v71, v69
	v_cvt_pk_bf16_f32 v68, v52, v53
	v_cvt_pk_bf16_f32 v69, v70, v71
	s_waitcnt lgkmcnt(4)
	v_mfma_f32_32x32x16_bf16 v[80:95], v[190:193], v[122:125], v[80:95]
	v_exp_f32_e32 v52, v56
	v_exp_f32_e32 v53, v57
	v_exp_f32_e32 v57, v58
	v_exp_f32_e32 v58, v59
	v_add_f32_e32 v54, v52, v54
	v_add_f32_e32 v55, v53, v55
	v_add_f32_e32 v59, v57, v72
	v_add_f32_e32 v70, v58, v73
	v_cvt_pk_bf16_f32 v56, v52, v53
	v_cvt_pk_bf16_f32 v57, v57, v58
	s_waitcnt lgkmcnt(3)
	v_mfma_f32_32x32x16_bf16 v[96:111], v[200:203], v[126:129], v[96:111]
	v_exp_f32_e32 v52, v76
	v_exp_f32_e32 v53, v77
	v_exp_f32_e32 v58, v78
	v_exp_f32_e32 v71, v79
	v_add_f32_e32 v54, v52, v54
	v_add_f32_e32 v55, v53, v55
	v_add_f32_e32 v59, v58, v59
	v_add_f32_e32 v72, v71, v70
	v_cvt_pk_bf16_f32 v70, v52, v53
	v_cvt_pk_bf16_f32 v71, v58, v71
	s_waitcnt lgkmcnt(2)
	v_mfma_f32_32x32x16_bf16 v[80:95], v[204:207], v[126:129], v[80:95]
	v_exp_f32_e32 v58, v60
	v_exp_f32_e32 v60, v61
	v_exp_f32_e32 v61, v62
	v_exp_f32_e32 v62, v63
	v_add_f32_e32 v52, v58, v54
	v_add_f32_e32 v53, v60, v55
	v_add_f32_e32 v54, v61, v59
	v_add_f32_e32 v55, v62, v72
	v_cvt_pk_bf16_f32 v58, v58, v60
	v_cvt_pk_bf16_f32 v59, v61, v62
	s_waitcnt lgkmcnt(1)
	v_mfma_f32_32x32x16_bf16 v[96:111], v[208:211], v[130:133], v[96:111]
	ds_read_b64_tr_b16 v[60:61], v180 offset:16384
	ds_read_b64_tr_b16 v[62:63], v180 offset:16896
	ds_read_b64_tr_b16 v[72:73], v180 offset:20480
	ds_read_b64_tr_b16 v[74:75], v180 offset:20992
	s_waitcnt lgkmcnt(4)
	v_mfma_f32_32x32x16_bf16 v[80:95], v[212:215], v[130:133], v[80:95]
	s_waitcnt lgkmcnt(2)
	v_mfma_f32_32x32x16_bf16 v[16:31], v[60:63], v[64:67], v[16:31]
	s_waitcnt lgkmcnt(0)
	v_mfma_f32_32x32x16_bf16 v[0:15], v[72:75], v[64:67], v[0:15]
	ds_read_b64_tr_b16 v[60:61], v180 offset:17408
	ds_read_b64_tr_b16 v[62:63], v180 offset:17920
	ds_read_b64_tr_b16 v[64:65], v180 offset:21504
	ds_read_b64_tr_b16 v[66:67], v180 offset:22016
	s_waitcnt lgkmcnt(2)
	v_mfma_f32_32x32x16_bf16 v[16:31], v[60:63], v[68:71], v[16:31]
	s_waitcnt lgkmcnt(0)
	v_mfma_f32_32x32x16_bf16 v[0:15], v[64:67], v[68:71], v[0:15]
	ds_read_b64_tr_b16 v[60:61], v180 offset:18432
	ds_read_b64_tr_b16 v[62:63], v180 offset:18944
	ds_read_b64_tr_b16 v[64:65], v180 offset:22528
	ds_read_b64_tr_b16 v[66:67], v180 offset:23040
	s_waitcnt lgkmcnt(2)
	v_mfma_f32_32x32x16_bf16 v[16:31], v[60:63], v[48:51], v[16:31]
	s_waitcnt lgkmcnt(0)
	v_mfma_f32_32x32x16_bf16 v[0:15], v[64:67], v[48:51], v[0:15]
	ds_read_b64_tr_b16 v[48:49], v180 offset:19456
	ds_read_b64_tr_b16 v[50:51], v180 offset:19968
	ds_read_b64_tr_b16 v[60:61], v180 offset:23552
	ds_read_b64_tr_b16 v[62:63], v180 offset:24064
	s_waitcnt lgkmcnt(2)
	v_mfma_f32_32x32x16_bf16 v[16:31], v[48:51], v[56:59], v[16:31]
	s_waitcnt lgkmcnt(0)
	v_mfma_f32_32x32x16_bf16 v[0:15], v[60:63], v[56:59], v[0:15]
	v_add_f32_e32 v182, v52, v53
	v_add_f32_e32 v183, v54, v55
	v_add_f32_e32 v182, v182, v183
	v_add_f32_e32 v169, v169, v182
	s_waitcnt vmcnt(2)
	s_waitcnt lgkmcnt(0)
	s_barrier
	s_add_i32 m0, s40, 0
	s_nop 0
	global_load_lds_dwordx4 v174, s[84:85]
	s_add_i32 m0, s41, 24576
	s_nop 0
	global_load_lds_dwordx4 v172, s[82:83]
	s_add_u32 s84, s84, 0x48000
	s_addc_u32 s85, s85, 0
	s_add_u32 s82, s82, 0x48000
	s_addc_u32 s83, s83, 0
	ds_read_b128 v[182:185], v114 offset:49152
	ds_read_b128 v[186:189], v114 offset:53248
	ds_read_b128 v[190:193], v115 offset:49152
	ds_read_b128 v[200:203], v115 offset:53248
	ds_read_b128 v[204:207], v116 offset:49152
	ds_read_b128 v[208:211], v116 offset:53248
	ds_read_b128 v[212:215], v117 offset:49152
	ds_read_b128 v[146:149], v117 offset:53248
	v_exp_f32_e32 v64, v96
	v_exp_f32_e32 v65, v97
	v_exp_f32_e32 v66, v98
	v_exp_f32_e32 v67, v99
	v_cvt_pk_bf16_f32 v96, v64, v65
	v_cvt_pk_bf16_f32 v97, v66, v67
	v_exp_f32_e32 v68, v80
	v_exp_f32_e32 v69, v81
	v_exp_f32_e32 v70, v82
	v_exp_f32_e32 v71, v83
	v_cvt_pk_bf16_f32 v80, v68, v69
	v_cvt_pk_bf16_f32 v81, v70, v71
	v_add_f32_e32 v68, v68, v64
	v_add_f32_e32 v69, v69, v65
	v_add_f32_e32 v82, v70, v66
	v_add_f32_e32 v83, v71, v67
	v_exp_f32_e32 v98, v100
	v_exp_f32_e32 v99, v101
	v_exp_f32_e32 v100, v102
	v_exp_f32_e32 v101, v103
	v_add_f32_e32 v102, v98, v68
	v_add_f32_e32 v103, v99, v69
	s_waitcnt lgkmcnt(7)
	v_mfma_f32_32x32x16_bf16 v[64:79], v[182:185], v[118:121], v[32:47]
	v_add_f32_e32 v82, v100, v82
	v_add_f32_e32 v83, v101, v83
	v_cvt_pk_bf16_f32 v98, v98, v99
	v_cvt_pk_bf16_f32 v99, v100, v101
	s_waitcnt lgkmcnt(6)
	v_mfma_f32_32x32x16_bf16 v[48:63], v[186:189], v[118:121], v[32:47]
	v_exp_f32_e32 v84, v84
	v_exp_f32_e32 v85, v85
	v_exp_f32_e32 v86, v86
	v_exp_f32_e32 v87, v87
	v_add_f32_e32 v100, v84, v102
	v_add_f32_e32 v101, v85, v103
	v_add_f32_e32 v102, v86, v82
	v_add_f32_e32 v103, v87, v83
	v_cvt_pk_bf16_f32 v82, v84, v85
	v_cvt_pk_bf16_f32 v83, v86, v87
	s_waitcnt lgkmcnt(5)
	v_mfma_f32_32x32x16_bf16 v[64:79], v[190:193], v[122:125], v[64:79]
	v_exp_f32_e32 v84, v104
	v_exp_f32_e32 v85, v105
	v_exp_f32_e32 v86, v106
	v_exp_f32_e32 v87, v107
	v_add_f32_e32 v104, v84, v100
	v_add_f32_e32 v105, v85, v101
	v_add_f32_e32 v102, v86, v102
	v_add_f32_e32 v103, v87, v103
	v_cvt_pk_bf16_f32 v100, v84, v85
	v_cvt_pk_bf16_f32 v101, v86, v87
	s_waitcnt lgkmcnt(4)
	v_mfma_f32_32x32x16_bf16 v[48:63], v[200:203], v[122:125], v[48:63]
	v_exp_f32_e32 v84, v88
	v_exp_f32_e32 v85, v89
	v_exp_f32_e32 v86, v90
	v_exp_f32_e32 v87, v91
	v_add_f32_e32 v90, v84, v104
	v_add_f32_e32 v91, v85, v105
	v_add_f32_e32 v102, v86, v102
	v_add_f32_e32 v103, v87, v103
	v_cvt_pk_bf16_f32 v88, v84, v85
	v_cvt_pk_bf16_f32 v89, v86, v87
	s_waitcnt lgkmcnt(3)
	v_mfma_f32_32x32x16_bf16 v[64:79], v[204:207], v[126:129], v[64:79]
	v_exp_f32_e32 v84, v108
	v_exp_f32_e32 v85, v109
	v_exp_f32_e32 v86, v110
	v_exp_f32_e32 v87, v111
	v_add_f32_e32 v90, v84, v90
	v_add_f32_e32 v91, v85, v91
	v_add_f32_e32 v104, v86, v102
	v_add_f32_e32 v105, v87, v103
	v_cvt_pk_bf16_f32 v102, v84, v85
	v_cvt_pk_bf16_f32 v103, v86, v87
	s_waitcnt lgkmcnt(2)
	v_mfma_f32_32x32x16_bf16 v[48:63], v[208:211], v[126:129], v[48:63]
	v_exp_f32_e32 v92, v92
	v_exp_f32_e32 v93, v93
	v_exp_f32_e32 v94, v94
	v_exp_f32_e32 v95, v95
	v_add_f32_e32 v84, v92, v90
	v_add_f32_e32 v85, v93, v91
	v_add_f32_e32 v86, v94, v104
	v_add_f32_e32 v87, v95, v105
	v_cvt_pk_bf16_f32 v90, v92, v93
	v_cvt_pk_bf16_f32 v91, v94, v95
	s_waitcnt lgkmcnt(1)
	v_mfma_f32_32x32x16_bf16 v[64:79], v[212:215], v[130:133], v[64:79]
	ds_read_b64_tr_b16 v[92:93], v180 offset:24576
	ds_read_b64_tr_b16 v[94:95], v180 offset:25088
	ds_read_b64_tr_b16 v[104:105], v180 offset:28672
	ds_read_b64_tr_b16 v[106:107], v180 offset:29184
	s_waitcnt lgkmcnt(4)
	v_mfma_f32_32x32x16_bf16 v[48:63], v[146:149], v[130:133], v[48:63]
	s_waitcnt lgkmcnt(2)
	v_mfma_f32_32x32x16_bf16 v[16:31], v[92:95], v[96:99], v[16:31]
	s_waitcnt lgkmcnt(0)
	v_mfma_f32_32x32x16_bf16 v[0:15], v[104:107], v[96:99], v[0:15]
	ds_read_b64_tr_b16 v[92:93], v180 offset:25600
	ds_read_b64_tr_b16 v[94:95], v180 offset:26112
	ds_read_b64_tr_b16 v[96:97], v180 offset:29696
	ds_read_b64_tr_b16 v[98:99], v180 offset:30208
	s_waitcnt lgkmcnt(2)
	v_mfma_f32_32x32x16_bf16 v[16:31], v[92:95], v[100:103], v[16:31]
	s_waitcnt lgkmcnt(0)
	v_mfma_f32_32x32x16_bf16 v[0:15], v[96:99], v[100:103], v[0:15]
	ds_read_b64_tr_b16 v[92:93], v180 offset:26624
	ds_read_b64_tr_b16 v[94:95], v180 offset:27136
	ds_read_b64_tr_b16 v[96:97], v180 offset:30720
	ds_read_b64_tr_b16 v[98:99], v180 offset:31232
	s_waitcnt lgkmcnt(2)
	v_mfma_f32_32x32x16_bf16 v[16:31], v[92:95], v[80:83], v[16:31]
	s_waitcnt lgkmcnt(0)
	v_mfma_f32_32x32x16_bf16 v[0:15], v[96:99], v[80:83], v[0:15]
	ds_read_b64_tr_b16 v[80:81], v180 offset:27648
	ds_read_b64_tr_b16 v[82:83], v180 offset:28160
	ds_read_b64_tr_b16 v[92:93], v180 offset:31744
	ds_read_b64_tr_b16 v[94:95], v180 offset:32256
	s_waitcnt lgkmcnt(2)
	v_mfma_f32_32x32x16_bf16 v[16:31], v[80:83], v[88:91], v[16:31]
	s_waitcnt lgkmcnt(0)
	v_mfma_f32_32x32x16_bf16 v[0:15], v[92:95], v[88:91], v[0:15]
	v_add_f32_e32 v182, v84, v85
	v_add_f32_e32 v183, v86, v87
	v_add_f32_e32 v182, v182, v183
	v_add_f32_e32 v169, v169, v182
	s_waitcnt vmcnt(2)
	s_waitcnt lgkmcnt(0)
	s_barrier
	s_add_i32 m0, s40, 8192
	s_nop 0
	global_load_lds_dwordx4 v174, s[84:85]
	s_add_i32 m0, s41, 0
	s_nop 0
	global_load_lds_dwordx4 v172, s[82:83]
	s_add_u32 s84, s84, 0x48000
	s_addc_u32 s85, s85, 0
	s_add_u32 s82, s82, 0x48000
	s_addc_u32 s83, s83, 0
	ds_read_b128 v[80:83], v114 offset:57344
	ds_read_b128 v[182:185], v114 offset:61440
	ds_read_b128 v[186:189], v115 offset:57344
	ds_read_b128 v[190:193], v115 offset:61440
	ds_read_b128 v[200:203], v116 offset:57344
	ds_read_b128 v[204:207], v116 offset:61440
	ds_read_b128 v[208:211], v117 offset:57344
	ds_read_b128 v[212:215], v117 offset:61440
	v_exp_f32_e32 v64, v64
	v_exp_f32_e32 v65, v65
	v_exp_f32_e32 v66, v66
	v_exp_f32_e32 v67, v67
	v_exp_f32_e32 v48, v48
	v_exp_f32_e32 v49, v49
	v_exp_f32_e32 v50, v50
	v_exp_f32_e32 v51, v51
	v_add_f32_e32 v84, v50, v66
	v_add_f32_e32 v85, v51, v67
	v_add_f32_e32 v86, v48, v64
	v_add_f32_e32 v87, v49, v65
	v_cvt_pk_bf16_f32 v64, v64, v65
	v_cvt_pk_bf16_f32 v65, v66, v67
	v_cvt_pk_bf16_f32 v48, v48, v49
	v_cvt_pk_bf16_f32 v49, v50, v51
	s_waitcnt lgkmcnt(7)
	v_mfma_f32_32x32x16_bf16 v[96:111], v[80:83], v[118:121], v[32:47]
	v_exp_f32_e32 v50, v68
	v_exp_f32_e32 v51, v69
	v_exp_f32_e32 v68, v70
	v_exp_f32_e32 v69, v71
	v_add_f32_e32 v70, v50, v86
	v_add_f32_e32 v71, v51, v87
	v_add_f32_e32 v181, v68, v84
	v_add_f32_e32 v228, v69, v85
	v_cvt_pk_bf16_f32 v66, v50, v51
	v_cvt_pk_bf16_f32 v67, v68, v69
	s_waitcnt lgkmcnt(6)
	v_mfma_f32_32x32x16_bf16 v[80:95], v[182:185], v[118:121], v[32:47]
	v_exp_f32_e32 v50, v52
	v_exp_f32_e32 v51, v53
	v_exp_f32_e32 v52, v54
	v_exp_f32_e32 v53, v55
	v_add_f32_e32 v54, v50, v70
	v_add_f32_e32 v55, v51, v71
	v_add_f32_e32 v68, v52, v181
	v_add_f32_e32 v69, v53, v228
	v_cvt_pk_bf16_f32 v50, v50, v51
	v_cvt_pk_bf16_f32 v51, v52, v53
	s_waitcnt lgkmcnt(5)
	v_mfma_f32_32x32x16_bf16 v[96:111], v[186:189], v[122:125], v[96:111]
	v_exp_f32_e32 v52, v72
	v_exp_f32_e32 v53, v73
	v_exp_f32_e32 v70, v74
	v_exp_f32_e32 v71, v75
	v_add_f32_e32 v54, v52, v54
	v_add_f32_e32 v55, v53, v55
	v_add_f32_e32 v72, v70, v68
	v_add_f32_e32 v73, v71, v69
	v_cvt_pk_bf16_f32 v68, v52, v53
	v_cvt_pk_bf16_f32 v69, v70, v71
	s_waitcnt lgkmcnt(4)
	v_mfma_f32_32x32x16_bf16 v[80:95], v[190:193], v[122:125], v[80:95]
	v_exp_f32_e32 v52, v56
	v_exp_f32_e32 v53, v57
	v_exp_f32_e32 v57, v58
	v_exp_f32_e32 v58, v59
	v_add_f32_e32 v54, v52, v54
	v_add_f32_e32 v55, v53, v55
	v_add_f32_e32 v59, v57, v72
	v_add_f32_e32 v70, v58, v73
	v_cvt_pk_bf16_f32 v56, v52, v53
	v_cvt_pk_bf16_f32 v57, v57, v58
	s_waitcnt lgkmcnt(3)
	v_mfma_f32_32x32x16_bf16 v[96:111], v[200:203], v[126:129], v[96:111]
	v_exp_f32_e32 v52, v76
	v_exp_f32_e32 v53, v77
	v_exp_f32_e32 v58, v78
	v_exp_f32_e32 v71, v79
	v_add_f32_e32 v54, v52, v54
	v_add_f32_e32 v55, v53, v55
	v_add_f32_e32 v59, v58, v59
	v_add_f32_e32 v72, v71, v70
	v_cvt_pk_bf16_f32 v70, v52, v53
	v_cvt_pk_bf16_f32 v71, v58, v71
	s_waitcnt lgkmcnt(2)
	v_mfma_f32_32x32x16_bf16 v[80:95], v[204:207], v[126:129], v[80:95]
	v_exp_f32_e32 v58, v60
	v_exp_f32_e32 v60, v61
	v_exp_f32_e32 v61, v62
	v_exp_f32_e32 v62, v63
	v_add_f32_e32 v52, v58, v54
	v_add_f32_e32 v53, v60, v55
	v_add_f32_e32 v54, v61, v59
	v_add_f32_e32 v55, v62, v72
	v_cvt_pk_bf16_f32 v58, v58, v60
	v_cvt_pk_bf16_f32 v59, v61, v62
	s_waitcnt lgkmcnt(1)
	v_mfma_f32_32x32x16_bf16 v[96:111], v[208:211], v[130:133], v[96:111]
	ds_read_b64_tr_b16 v[60:61], v180 offset:32768
	ds_read_b64_tr_b16 v[62:63], v180 offset:33280
	ds_read_b64_tr_b16 v[72:73], v180 offset:36864
	ds_read_b64_tr_b16 v[74:75], v180 offset:37376
	s_waitcnt lgkmcnt(4)
	v_mfma_f32_32x32x16_bf16 v[80:95], v[212:215], v[130:133], v[80:95]
	s_waitcnt lgkmcnt(2)
	v_mfma_f32_32x32x16_bf16 v[16:31], v[60:63], v[64:67], v[16:31]
	s_waitcnt lgkmcnt(0)
	v_mfma_f32_32x32x16_bf16 v[0:15], v[72:75], v[64:67], v[0:15]
	ds_read_b64_tr_b16 v[60:61], v180 offset:33792
	ds_read_b64_tr_b16 v[62:63], v180 offset:34304
	ds_read_b64_tr_b16 v[64:65], v180 offset:37888
	ds_read_b64_tr_b16 v[66:67], v180 offset:38400
	s_waitcnt lgkmcnt(2)
	v_mfma_f32_32x32x16_bf16 v[16:31], v[60:63], v[68:71], v[16:31]
	s_waitcnt lgkmcnt(0)
	v_mfma_f32_32x32x16_bf16 v[0:15], v[64:67], v[68:71], v[0:15]
	ds_read_b64_tr_b16 v[60:61], v180 offset:34816
	ds_read_b64_tr_b16 v[62:63], v180 offset:35328
	ds_read_b64_tr_b16 v[64:65], v180 offset:38912
	ds_read_b64_tr_b16 v[66:67], v180 offset:39424
	s_waitcnt lgkmcnt(2)
	v_mfma_f32_32x32x16_bf16 v[16:31], v[60:63], v[48:51], v[16:31]
	s_waitcnt lgkmcnt(0)
	v_mfma_f32_32x32x16_bf16 v[0:15], v[64:67], v[48:51], v[0:15]
	ds_read_b64_tr_b16 v[48:49], v180 offset:35840
	ds_read_b64_tr_b16 v[50:51], v180 offset:36352
	ds_read_b64_tr_b16 v[60:61], v180 offset:39936
	ds_read_b64_tr_b16 v[62:63], v180 offset:40448
	s_waitcnt lgkmcnt(2)
	v_mfma_f32_32x32x16_bf16 v[16:31], v[48:51], v[56:59], v[16:31]
	s_waitcnt lgkmcnt(0)
	v_mfma_f32_32x32x16_bf16 v[0:15], v[60:63], v[56:59], v[0:15]
	v_add_f32_e32 v182, v52, v53
	v_add_f32_e32 v183, v54, v55
	v_add_f32_e32 v182, v182, v183
	v_add_f32_e32 v169, v169, v182
	s_waitcnt vmcnt(2)
	s_waitcnt lgkmcnt(0)
	s_barrier
	s_add_i32 m0, s40, 49152
	s_nop 0
	global_load_lds_dwordx4 v174, s[84:85]
	s_add_i32 m0, s41, 8192
	s_nop 0
	global_load_lds_dwordx4 v172, s[82:83]
	s_add_u32 s84, s84, 0x48000
	s_addc_u32 s85, s85, 0
	s_add_u32 s82, s82, 0x48000
	s_addc_u32 s83, s83, 0
	ds_read_b128 v[182:185], v114
	ds_read_b128 v[186:189], v114 offset:4096
	ds_read_b128 v[190:193], v115
	ds_read_b128 v[200:203], v115 offset:4096
	ds_read_b128 v[204:207], v116
	ds_read_b128 v[208:211], v116 offset:4096
	ds_read_b128 v[212:215], v117
	ds_read_b128 v[146:149], v117 offset:4096
	v_exp_f32_e32 v64, v96
	v_exp_f32_e32 v65, v97
	v_exp_f32_e32 v66, v98
	v_exp_f32_e32 v67, v99
	v_cvt_pk_bf16_f32 v96, v64, v65
	v_cvt_pk_bf16_f32 v97, v66, v67
	v_exp_f32_e32 v68, v80
	v_exp_f32_e32 v69, v81
	v_exp_f32_e32 v70, v82
	v_exp_f32_e32 v71, v83
	v_cvt_pk_bf16_f32 v80, v68, v69
	v_cvt_pk_bf16_f32 v81, v70, v71
	v_add_f32_e32 v68, v68, v64
	v_add_f32_e32 v69, v69, v65
	v_add_f32_e32 v82, v70, v66
	v_add_f32_e32 v83, v71, v67
	v_exp_f32_e32 v98, v100
	v_exp_f32_e32 v99, v101
	v_exp_f32_e32 v100, v102
	v_exp_f32_e32 v101, v103
	v_add_f32_e32 v102, v98, v68
	v_add_f32_e32 v103, v99, v69
	s_waitcnt lgkmcnt(7)
	v_mfma_f32_32x32x16_bf16 v[64:79], v[182:185], v[118:121], v[32:47]
	v_add_f32_e32 v82, v100, v82
	v_add_f32_e32 v83, v101, v83
	v_cvt_pk_bf16_f32 v98, v98, v99
	v_cvt_pk_bf16_f32 v99, v100, v101
	s_waitcnt lgkmcnt(6)
	v_mfma_f32_32x32x16_bf16 v[48:63], v[186:189], v[118:121], v[32:47]
	v_exp_f32_e32 v84, v84
	v_exp_f32_e32 v85, v85
	v_exp_f32_e32 v86, v86
	v_exp_f32_e32 v87, v87
	v_add_f32_e32 v100, v84, v102
	v_add_f32_e32 v101, v85, v103
	v_add_f32_e32 v102, v86, v82
	v_add_f32_e32 v103, v87, v83
	v_cvt_pk_bf16_f32 v82, v84, v85
	v_cvt_pk_bf16_f32 v83, v86, v87
	s_waitcnt lgkmcnt(5)
	v_mfma_f32_32x32x16_bf16 v[64:79], v[190:193], v[122:125], v[64:79]
	v_exp_f32_e32 v84, v104
	v_exp_f32_e32 v85, v105
	v_exp_f32_e32 v86, v106
	v_exp_f32_e32 v87, v107
	v_add_f32_e32 v104, v84, v100
	v_add_f32_e32 v105, v85, v101
	v_add_f32_e32 v102, v86, v102
	v_add_f32_e32 v103, v87, v103
	v_cvt_pk_bf16_f32 v100, v84, v85
	v_cvt_pk_bf16_f32 v101, v86, v87
	s_waitcnt lgkmcnt(4)
	v_mfma_f32_32x32x16_bf16 v[48:63], v[200:203], v[122:125], v[48:63]
	v_exp_f32_e32 v84, v88
	v_exp_f32_e32 v85, v89
	v_exp_f32_e32 v86, v90
	v_exp_f32_e32 v87, v91
	v_add_f32_e32 v90, v84, v104
	v_add_f32_e32 v91, v85, v105
	v_add_f32_e32 v102, v86, v102
	v_add_f32_e32 v103, v87, v103
	v_cvt_pk_bf16_f32 v88, v84, v85
	v_cvt_pk_bf16_f32 v89, v86, v87
	s_waitcnt lgkmcnt(3)
	v_mfma_f32_32x32x16_bf16 v[64:79], v[204:207], v[126:129], v[64:79]
	v_exp_f32_e32 v84, v108
	v_exp_f32_e32 v85, v109
	v_exp_f32_e32 v86, v110
	v_exp_f32_e32 v87, v111
	v_add_f32_e32 v90, v84, v90
	v_add_f32_e32 v91, v85, v91
	v_add_f32_e32 v104, v86, v102
	v_add_f32_e32 v105, v87, v103
	v_cvt_pk_bf16_f32 v102, v84, v85
	v_cvt_pk_bf16_f32 v103, v86, v87
	s_waitcnt lgkmcnt(2)
	v_mfma_f32_32x32x16_bf16 v[48:63], v[208:211], v[126:129], v[48:63]
	v_exp_f32_e32 v92, v92
	v_exp_f32_e32 v93, v93
	v_exp_f32_e32 v94, v94
	v_exp_f32_e32 v95, v95
	v_add_f32_e32 v84, v92, v90
	v_add_f32_e32 v85, v93, v91
	v_add_f32_e32 v86, v94, v104
	v_add_f32_e32 v87, v95, v105
	v_cvt_pk_bf16_f32 v90, v92, v93
	v_cvt_pk_bf16_f32 v91, v94, v95
	s_waitcnt lgkmcnt(1)
	v_mfma_f32_32x32x16_bf16 v[64:79], v[212:215], v[130:133], v[64:79]
	ds_read_b64_tr_b16 v[92:93], v180 offset:40960
	ds_read_b64_tr_b16 v[94:95], v180 offset:41472
	ds_read_b64_tr_b16 v[104:105], v180 offset:45056
	ds_read_b64_tr_b16 v[106:107], v180 offset:45568
	s_waitcnt lgkmcnt(4)
	v_mfma_f32_32x32x16_bf16 v[48:63], v[146:149], v[130:133], v[48:63]
	s_waitcnt lgkmcnt(2)
	v_mfma_f32_32x32x16_bf16 v[16:31], v[92:95], v[96:99], v[16:31]
	s_waitcnt lgkmcnt(0)
	v_mfma_f32_32x32x16_bf16 v[0:15], v[104:107], v[96:99], v[0:15]
	ds_read_b64_tr_b16 v[92:93], v180 offset:41984
	ds_read_b64_tr_b16 v[94:95], v180 offset:42496
	ds_read_b64_tr_b16 v[96:97], v180 offset:46080
	ds_read_b64_tr_b16 v[98:99], v180 offset:46592
	s_waitcnt lgkmcnt(2)
	v_mfma_f32_32x32x16_bf16 v[16:31], v[92:95], v[100:103], v[16:31]
	s_waitcnt lgkmcnt(0)
	v_mfma_f32_32x32x16_bf16 v[0:15], v[96:99], v[100:103], v[0:15]
	ds_read_b64_tr_b16 v[92:93], v180 offset:43008
	ds_read_b64_tr_b16 v[94:95], v180 offset:43520
	ds_read_b64_tr_b16 v[96:97], v180 offset:47104
	ds_read_b64_tr_b16 v[98:99], v180 offset:47616
	s_waitcnt lgkmcnt(2)
	v_mfma_f32_32x32x16_bf16 v[16:31], v[92:95], v[80:83], v[16:31]
	s_waitcnt lgkmcnt(0)
	v_mfma_f32_32x32x16_bf16 v[0:15], v[96:99], v[80:83], v[0:15]
	ds_read_b64_tr_b16 v[80:81], v180 offset:44032
	ds_read_b64_tr_b16 v[82:83], v180 offset:44544
	ds_read_b64_tr_b16 v[92:93], v180 offset:48128
	ds_read_b64_tr_b16 v[94:95], v180 offset:48640
	s_waitcnt lgkmcnt(2)
	v_mfma_f32_32x32x16_bf16 v[16:31], v[80:83], v[88:91], v[16:31]
	s_waitcnt lgkmcnt(0)
	v_mfma_f32_32x32x16_bf16 v[0:15], v[92:95], v[88:91], v[0:15]
	v_add_f32_e32 v182, v84, v85
	v_add_f32_e32 v183, v86, v87
	v_add_f32_e32 v182, v182, v183
	v_add_f32_e32 v169, v169, v182
	s_waitcnt vmcnt(2)
	s_waitcnt lgkmcnt(0)
	s_barrier
	s_add_i32 s80, s80, 4
	s_cmp_lt_u32 s80, 60
	s_cbranch_scc1 .Lfa_g0_loop
	s_add_i32 m0, s40, 57344
	s_nop 0
	global_load_lds_dwordx4 v174, s[84:85]
	s_add_i32 m0, s41, 16384
	s_nop 0
	global_load_lds_dwordx4 v172, s[82:83]
	s_add_u32 s84, s84, 0x48000
	s_addc_u32 s85, s85, 0
	s_add_u32 s82, s82, 0x48000
	s_addc_u32 s83, s83, 0
	ds_read_b128 v[80:83], v114 offset:8192
	ds_read_b128 v[182:185], v114 offset:12288
	ds_read_b128 v[186:189], v115 offset:8192
	ds_read_b128 v[190:193], v115 offset:12288
	ds_read_b128 v[200:203], v116 offset:8192
	ds_read_b128 v[204:207], v116 offset:12288
	ds_read_b128 v[208:211], v117 offset:8192
	ds_read_b128 v[212:215], v117 offset:12288
	v_exp_f32_e32 v64, v64
	v_exp_f32_e32 v65, v65
	v_exp_f32_e32 v66, v66
	v_exp_f32_e32 v67, v67
	v_exp_f32_e32 v48, v48
	v_exp_f32_e32 v49, v49
	v_exp_f32_e32 v50, v50
	v_exp_f32_e32 v51, v51
	v_add_f32_e32 v84, v50, v66
	v_add_f32_e32 v85, v51, v67
	v_add_f32_e32 v86, v48, v64
	v_add_f32_e32 v87, v49, v65
	v_cvt_pk_bf16_f32 v64, v64, v65
	v_cvt_pk_bf16_f32 v65, v66, v67
	v_cvt_pk_bf16_f32 v48, v48, v49
	v_cvt_pk_bf16_f32 v49, v50, v51
	s_waitcnt lgkmcnt(7)
	v_mfma_f32_32x32x16_bf16 v[96:111], v[80:83], v[118:121], v[32:47]
	v_exp_f32_e32 v50, v68
	v_exp_f32_e32 v51, v69
	v_exp_f32_e32 v68, v70
	v_exp_f32_e32 v69, v71
	v_add_f32_e32 v70, v50, v86
	v_add_f32_e32 v71, v51, v87
	v_add_f32_e32 v181, v68, v84
	v_add_f32_e32 v228, v69, v85
	v_cvt_pk_bf16_f32 v66, v50, v51
	v_cvt_pk_bf16_f32 v67, v68, v69
	s_waitcnt lgkmcnt(6)
	v_mfma_f32_32x32x16_bf16 v[80:95], v[182:185], v[118:121], v[32:47]
	v_exp_f32_e32 v50, v52
	v_exp_f32_e32 v51, v53
	v_exp_f32_e32 v52, v54
	v_exp_f32_e32 v53, v55
	v_add_f32_e32 v54, v50, v70
	v_add_f32_e32 v55, v51, v71
	v_add_f32_e32 v68, v52, v181
	v_add_f32_e32 v69, v53, v228
	v_cvt_pk_bf16_f32 v50, v50, v51
	v_cvt_pk_bf16_f32 v51, v52, v53
	s_waitcnt lgkmcnt(5)
	v_mfma_f32_32x32x16_bf16 v[96:111], v[186:189], v[122:125], v[96:111]
	v_exp_f32_e32 v52, v72
	v_exp_f32_e32 v53, v73
	v_exp_f32_e32 v70, v74
	v_exp_f32_e32 v71, v75
	v_add_f32_e32 v54, v52, v54
	v_add_f32_e32 v55, v53, v55
	v_add_f32_e32 v72, v70, v68
	v_add_f32_e32 v73, v71, v69
	v_cvt_pk_bf16_f32 v68, v52, v53
	v_cvt_pk_bf16_f32 v69, v70, v71
	s_waitcnt lgkmcnt(4)
	v_mfma_f32_32x32x16_bf16 v[80:95], v[190:193], v[122:125], v[80:95]
	v_exp_f32_e32 v52, v56
	v_exp_f32_e32 v53, v57
	v_exp_f32_e32 v57, v58
	v_exp_f32_e32 v58, v59
	v_add_f32_e32 v54, v52, v54
	v_add_f32_e32 v55, v53, v55
	v_add_f32_e32 v59, v57, v72
	v_add_f32_e32 v70, v58, v73
	v_cvt_pk_bf16_f32 v56, v52, v53
	v_cvt_pk_bf16_f32 v57, v57, v58
	s_waitcnt lgkmcnt(3)
	v_mfma_f32_32x32x16_bf16 v[96:111], v[200:203], v[126:129], v[96:111]
	v_exp_f32_e32 v52, v76
	v_exp_f32_e32 v53, v77
	v_exp_f32_e32 v58, v78
	v_exp_f32_e32 v71, v79
	v_add_f32_e32 v54, v52, v54
	v_add_f32_e32 v55, v53, v55
	v_add_f32_e32 v59, v58, v59
	v_add_f32_e32 v72, v71, v70
	v_cvt_pk_bf16_f32 v70, v52, v53
	v_cvt_pk_bf16_f32 v71, v58, v71
	s_waitcnt lgkmcnt(2)
	v_mfma_f32_32x32x16_bf16 v[80:95], v[204:207], v[126:129], v[80:95]
	v_exp_f32_e32 v58, v60
	v_exp_f32_e32 v60, v61
	v_exp_f32_e32 v61, v62
	v_exp_f32_e32 v62, v63
	v_add_f32_e32 v52, v58, v54
	v_add_f32_e32 v53, v60, v55
	v_add_f32_e32 v54, v61, v59
	v_add_f32_e32 v55, v62, v72
	v_cvt_pk_bf16_f32 v58, v58, v60
	v_cvt_pk_bf16_f32 v59, v61, v62
	s_waitcnt lgkmcnt(1)
	v_mfma_f32_32x32x16_bf16 v[96:111], v[208:211], v[130:133], v[96:111]
	ds_read_b64_tr_b16 v[60:61], v180 offset:16384
	ds_read_b64_tr_b16 v[62:63], v180 offset:16896
	ds_read_b64_tr_b16 v[72:73], v180 offset:20480
	ds_read_b64_tr_b16 v[74:75], v180 offset:20992
	s_waitcnt lgkmcnt(4)
	v_mfma_f32_32x32x16_bf16 v[80:95], v[212:215], v[130:133], v[80:95]
	s_waitcnt lgkmcnt(2)
	v_mfma_f32_32x32x16_bf16 v[16:31], v[60:63], v[64:67], v[16:31]
	s_waitcnt lgkmcnt(0)
	v_mfma_f32_32x32x16_bf16 v[0:15], v[72:75], v[64:67], v[0:15]
	ds_read_b64_tr_b16 v[60:61], v180 offset:17408
	ds_read_b64_tr_b16 v[62:63], v180 offset:17920
	ds_read_b64_tr_b16 v[64:65], v180 offset:21504
	ds_read_b64_tr_b16 v[66:67], v180 offset:22016
	s_waitcnt lgkmcnt(2)
	v_mfma_f32_32x32x16_bf16 v[16:31], v[60:63], v[68:71], v[16:31]
	s_waitcnt lgkmcnt(0)
	v_mfma_f32_32x32x16_bf16 v[0:15], v[64:67], v[68:71], v[0:15]
	ds_read_b64_tr_b16 v[60:61], v180 offset:18432
	ds_read_b64_tr_b16 v[62:63], v180 offset:18944
	ds_read_b64_tr_b16 v[64:65], v180 offset:22528
	ds_read_b64_tr_b16 v[66:67], v180 offset:23040
	s_waitcnt lgkmcnt(2)
	v_mfma_f32_32x32x16_bf16 v[16:31], v[60:63], v[48:51], v[16:31]
	s_waitcnt lgkmcnt(0)
	v_mfma_f32_32x32x16_bf16 v[0:15], v[64:67], v[48:51], v[0:15]
	ds_read_b64_tr_b16 v[48:49], v180 offset:19456
	ds_read_b64_tr_b16 v[50:51], v180 offset:19968
	ds_read_b64_tr_b16 v[60:61], v180 offset:23552
	ds_read_b64_tr_b16 v[62:63], v180 offset:24064
	s_waitcnt lgkmcnt(2)
	v_mfma_f32_32x32x16_bf16 v[16:31], v[48:51], v[56:59], v[16:31]
	s_waitcnt lgkmcnt(0)
	v_mfma_f32_32x32x16_bf16 v[0:15], v[60:63], v[56:59], v[0:15]
	v_add_f32_e32 v182, v52, v53
	v_add_f32_e32 v183, v54, v55
	v_add_f32_e32 v182, v182, v183
	v_add_f32_e32 v169, v169, v182
	s_waitcnt vmcnt(2)
	s_waitcnt lgkmcnt(0)
	s_barrier
	s_add_i32 m0, s41, 24576
	s_nop 0
	global_load_lds_dwordx4 v172, s[82:83]
	s_add_u32 s84, s84, 0x48000
	s_addc_u32 s85, s85, 0
	s_add_u32 s82, s82, 0x48000
	s_addc_u32 s83, s83, 0
	ds_read_b128 v[182:185], v114 offset:49152
	ds_read_b128 v[186:189], v114 offset:53248
	ds_read_b128 v[190:193], v115 offset:49152
	ds_read_b128 v[200:203], v115 offset:53248
	ds_read_b128 v[204:207], v116 offset:49152
	ds_read_b128 v[208:211], v116 offset:53248
	ds_read_b128 v[212:215], v117 offset:49152
	ds_read_b128 v[146:149], v117 offset:53248
	v_exp_f32_e32 v64, v96
	v_exp_f32_e32 v65, v97
	v_exp_f32_e32 v66, v98
	v_exp_f32_e32 v67, v99
	v_cvt_pk_bf16_f32 v96, v64, v65
	v_cvt_pk_bf16_f32 v97, v66, v67
	v_exp_f32_e32 v68, v80
	v_exp_f32_e32 v69, v81
	v_exp_f32_e32 v70, v82
	v_exp_f32_e32 v71, v83
	v_cvt_pk_bf16_f32 v80, v68, v69
	v_cvt_pk_bf16_f32 v81, v70, v71
	v_add_f32_e32 v68, v68, v64
	v_add_f32_e32 v69, v69, v65
	v_add_f32_e32 v82, v70, v66
	v_add_f32_e32 v83, v71, v67
	v_exp_f32_e32 v98, v100
	v_exp_f32_e32 v99, v101
	v_exp_f32_e32 v100, v102
	v_exp_f32_e32 v101, v103
	v_add_f32_e32 v102, v98, v68
	v_add_f32_e32 v103, v99, v69
	s_waitcnt lgkmcnt(7)
	v_mfma_f32_32x32x16_bf16 v[64:79], v[182:185], v[118:121], v[32:47]
	v_add_f32_e32 v82, v100, v82
	v_add_f32_e32 v83, v101, v83
	v_cvt_pk_bf16_f32 v98, v98, v99
	v_cvt_pk_bf16_f32 v99, v100, v101
	s_waitcnt lgkmcnt(6)
	v_mfma_f32_32x32x16_bf16 v[48:63], v[186:189], v[118:121], v[32:47]
	v_exp_f32_e32 v84, v84
	v_exp_f32_e32 v85, v85
	v_exp_f32_e32 v86, v86
	v_exp_f32_e32 v87, v87
	v_add_f32_e32 v100, v84, v102
	v_add_f32_e32 v101, v85, v103
	v_add_f32_e32 v102, v86, v82
	v_add_f32_e32 v103, v87, v83
	v_cvt_pk_bf16_f32 v82, v84, v85
	v_cvt_pk_bf16_f32 v83, v86, v87
	s_waitcnt lgkmcnt(5)
	v_mfma_f32_32x32x16_bf16 v[64:79], v[190:193], v[122:125], v[64:79]
	v_exp_f32_e32 v84, v104
	v_exp_f32_e32 v85, v105
	v_exp_f32_e32 v86, v106
	v_exp_f32_e32 v87, v107
	v_add_f32_e32 v104, v84, v100
	v_add_f32_e32 v105, v85, v101
	v_add_f32_e32 v102, v86, v102
	v_add_f32_e32 v103, v87, v103
	v_cvt_pk_bf16_f32 v100, v84, v85
	v_cvt_pk_bf16_f32 v101, v86, v87
	s_waitcnt lgkmcnt(4)
	v_mfma_f32_32x32x16_bf16 v[48:63], v[200:203], v[122:125], v[48:63]
	v_exp_f32_e32 v84, v88
	v_exp_f32_e32 v85, v89
	v_exp_f32_e32 v86, v90
	v_exp_f32_e32 v87, v91
	v_add_f32_e32 v90, v84, v104
	v_add_f32_e32 v91, v85, v105
	v_add_f32_e32 v102, v86, v102
	v_add_f32_e32 v103, v87, v103
	v_cvt_pk_bf16_f32 v88, v84, v85
	v_cvt_pk_bf16_f32 v89, v86, v87
	s_waitcnt lgkmcnt(3)
	v_mfma_f32_32x32x16_bf16 v[64:79], v[204:207], v[126:129], v[64:79]
	v_exp_f32_e32 v84, v108
	v_exp_f32_e32 v85, v109
	v_exp_f32_e32 v86, v110
	v_exp_f32_e32 v87, v111
	v_add_f32_e32 v90, v84, v90
	v_add_f32_e32 v91, v85, v91
	v_add_f32_e32 v104, v86, v102
	v_add_f32_e32 v105, v87, v103
	v_cvt_pk_bf16_f32 v102, v84, v85
	v_cvt_pk_bf16_f32 v103, v86, v87
	s_waitcnt lgkmcnt(2)
	v_mfma_f32_32x32x16_bf16 v[48:63], v[208:211], v[126:129], v[48:63]
	v_exp_f32_e32 v92, v92
	v_exp_f32_e32 v93, v93
	v_exp_f32_e32 v94, v94
	v_exp_f32_e32 v95, v95
	v_add_f32_e32 v84, v92, v90
	v_add_f32_e32 v85, v93, v91
	v_add_f32_e32 v86, v94, v104
	v_add_f32_e32 v87, v95, v105
	v_cvt_pk_bf16_f32 v90, v92, v93
	v_cvt_pk_bf16_f32 v91, v94, v95
	s_waitcnt lgkmcnt(1)
	v_mfma_f32_32x32x16_bf16 v[64:79], v[212:215], v[130:133], v[64:79]
	ds_read_b64_tr_b16 v[92:93], v180 offset:24576
	ds_read_b64_tr_b16 v[94:95], v180 offset:25088
	ds_read_b64_tr_b16 v[104:105], v180 offset:28672
	ds_read_b64_tr_b16 v[106:107], v180 offset:29184
	s_waitcnt lgkmcnt(4)
	v_mfma_f32_32x32x16_bf16 v[48:63], v[146:149], v[130:133], v[48:63]
	s_waitcnt lgkmcnt(2)
	v_mfma_f32_32x32x16_bf16 v[16:31], v[92:95], v[96:99], v[16:31]
	s_waitcnt lgkmcnt(0)
	v_mfma_f32_32x32x16_bf16 v[0:15], v[104:107], v[96:99], v[0:15]
	ds_read_b64_tr_b16 v[92:93], v180 offset:25600
	ds_read_b64_tr_b16 v[94:95], v180 offset:26112
	ds_read_b64_tr_b16 v[96:97], v180 offset:29696
	ds_read_b64_tr_b16 v[98:99], v180 offset:30208
	s_waitcnt lgkmcnt(2)
	v_mfma_f32_32x32x16_bf16 v[16:31], v[92:95], v[100:103], v[16:31]
	s_waitcnt lgkmcnt(0)
	v_mfma_f32_32x32x16_bf16 v[0:15], v[96:99], v[100:103], v[0:15]
	ds_read_b64_tr_b16 v[92:93], v180 offset:26624
	ds_read_b64_tr_b16 v[94:95], v180 offset:27136
	ds_read_b64_tr_b16 v[96:97], v180 offset:30720
	ds_read_b64_tr_b16 v[98:99], v180 offset:31232
	s_waitcnt lgkmcnt(2)
	v_mfma_f32_32x32x16_bf16 v[16:31], v[92:95], v[80:83], v[16:31]
	s_waitcnt lgkmcnt(0)
	v_mfma_f32_32x32x16_bf16 v[0:15], v[96:99], v[80:83], v[0:15]
	ds_read_b64_tr_b16 v[80:81], v180 offset:27648
	ds_read_b64_tr_b16 v[82:83], v180 offset:28160
	ds_read_b64_tr_b16 v[92:93], v180 offset:31744
	ds_read_b64_tr_b16 v[94:95], v180 offset:32256
	s_waitcnt lgkmcnt(2)
	v_mfma_f32_32x32x16_bf16 v[16:31], v[80:83], v[88:91], v[16:31]
	s_waitcnt lgkmcnt(0)
	v_mfma_f32_32x32x16_bf16 v[0:15], v[92:95], v[88:91], v[0:15]
	v_add_f32_e32 v182, v84, v85
	v_add_f32_e32 v183, v86, v87
	v_add_f32_e32 v182, v182, v183
	v_add_f32_e32 v169, v169, v182
	s_waitcnt vmcnt(1)
	s_waitcnt lgkmcnt(0)
	s_barrier
	s_add_u32 s84, s84, 0x48000
	s_addc_u32 s85, s85, 0
	s_add_u32 s82, s82, 0x48000
	s_addc_u32 s83, s83, 0
	ds_read_b128 v[80:83], v114 offset:57344
	ds_read_b128 v[182:185], v114 offset:61440
	ds_read_b128 v[186:189], v115 offset:57344
	ds_read_b128 v[190:193], v115 offset:61440
	ds_read_b128 v[200:203], v116 offset:57344
	ds_read_b128 v[204:207], v116 offset:61440
	ds_read_b128 v[208:211], v117 offset:57344
	ds_read_b128 v[212:215], v117 offset:61440
	v_exp_f32_e32 v64, v64
	v_exp_f32_e32 v65, v65
	v_exp_f32_e32 v66, v66
	v_exp_f32_e32 v67, v67
	v_exp_f32_e32 v48, v48
	v_exp_f32_e32 v49, v49
	v_exp_f32_e32 v50, v50
	v_exp_f32_e32 v51, v51
	v_add_f32_e32 v84, v50, v66
	v_add_f32_e32 v85, v51, v67
	v_add_f32_e32 v86, v48, v64
	v_add_f32_e32 v87, v49, v65
	v_cvt_pk_bf16_f32 v64, v64, v65
	v_cvt_pk_bf16_f32 v65, v66, v67
	v_cvt_pk_bf16_f32 v48, v48, v49
	v_cvt_pk_bf16_f32 v49, v50, v51
	s_waitcnt lgkmcnt(7)
	v_mfma_f32_32x32x16_bf16 v[96:111], v[80:83], v[118:121], v[32:47]
	v_exp_f32_e32 v50, v68
	v_exp_f32_e32 v51, v69
	v_exp_f32_e32 v68, v70
	v_exp_f32_e32 v69, v71
	v_add_f32_e32 v70, v50, v86
	v_add_f32_e32 v71, v51, v87
	v_add_f32_e32 v181, v68, v84
	v_add_f32_e32 v228, v69, v85
	v_cvt_pk_bf16_f32 v66, v50, v51
	v_cvt_pk_bf16_f32 v67, v68, v69
	s_waitcnt lgkmcnt(6)
	v_mfma_f32_32x32x16_bf16 v[80:95], v[182:185], v[118:121], v[32:47]
	v_exp_f32_e32 v50, v52
	v_exp_f32_e32 v51, v53
	v_exp_f32_e32 v52, v54
	v_exp_f32_e32 v53, v55
	v_add_f32_e32 v54, v50, v70
	v_add_f32_e32 v55, v51, v71
	v_add_f32_e32 v68, v52, v181
	v_add_f32_e32 v69, v53, v228
	v_cvt_pk_bf16_f32 v50, v50, v51
	v_cvt_pk_bf16_f32 v51, v52, v53
	s_waitcnt lgkmcnt(5)
	v_mfma_f32_32x32x16_bf16 v[96:111], v[186:189], v[122:125], v[96:111]
	v_exp_f32_e32 v52, v72
	v_exp_f32_e32 v53, v73
	v_exp_f32_e32 v70, v74
	v_exp_f32_e32 v71, v75
	v_add_f32_e32 v54, v52, v54
	v_add_f32_e32 v55, v53, v55
	v_add_f32_e32 v72, v70, v68
	v_add_f32_e32 v73, v71, v69
	v_cvt_pk_bf16_f32 v68, v52, v53
	v_cvt_pk_bf16_f32 v69, v70, v71
	s_waitcnt lgkmcnt(4)
	v_mfma_f32_32x32x16_bf16 v[80:95], v[190:193], v[122:125], v[80:95]
	v_exp_f32_e32 v52, v56
	v_exp_f32_e32 v53, v57
	v_exp_f32_e32 v57, v58
	v_exp_f32_e32 v58, v59
	v_add_f32_e32 v54, v52, v54
	v_add_f32_e32 v55, v53, v55
	v_add_f32_e32 v59, v57, v72
	v_add_f32_e32 v70, v58, v73
	v_cvt_pk_bf16_f32 v56, v52, v53
	v_cvt_pk_bf16_f32 v57, v57, v58
	s_waitcnt lgkmcnt(3)
	v_mfma_f32_32x32x16_bf16 v[96:111], v[200:203], v[126:129], v[96:111]
	v_exp_f32_e32 v52, v76
	v_exp_f32_e32 v53, v77
	v_exp_f32_e32 v58, v78
	v_exp_f32_e32 v71, v79
	v_add_f32_e32 v54, v52, v54
	v_add_f32_e32 v55, v53, v55
	v_add_f32_e32 v59, v58, v59
	v_add_f32_e32 v72, v71, v70
	v_cvt_pk_bf16_f32 v70, v52, v53
	v_cvt_pk_bf16_f32 v71, v58, v71
	s_waitcnt lgkmcnt(2)
	v_mfma_f32_32x32x16_bf16 v[80:95], v[204:207], v[126:129], v[80:95]
	v_exp_f32_e32 v58, v60
	v_exp_f32_e32 v60, v61
	v_exp_f32_e32 v61, v62
	v_exp_f32_e32 v62, v63
	v_add_f32_e32 v52, v58, v54
	v_add_f32_e32 v53, v60, v55
	v_add_f32_e32 v54, v61, v59
	v_add_f32_e32 v55, v62, v72
	v_cvt_pk_bf16_f32 v58, v58, v60
	v_cvt_pk_bf16_f32 v59, v61, v62
	s_waitcnt lgkmcnt(1)
	v_mfma_f32_32x32x16_bf16 v[96:111], v[208:211], v[130:133], v[96:111]
	ds_read_b64_tr_b16 v[60:61], v180 offset:32768
	ds_read_b64_tr_b16 v[62:63], v180 offset:33280
	ds_read_b64_tr_b16 v[72:73], v180 offset:36864
	ds_read_b64_tr_b16 v[74:75], v180 offset:37376
	s_waitcnt lgkmcnt(4)
	v_mfma_f32_32x32x16_bf16 v[80:95], v[212:215], v[130:133], v[80:95]
	s_waitcnt lgkmcnt(2)
	v_mfma_f32_32x32x16_bf16 v[16:31], v[60:63], v[64:67], v[16:31]
	s_waitcnt lgkmcnt(0)
	v_mfma_f32_32x32x16_bf16 v[0:15], v[72:75], v[64:67], v[0:15]
	ds_read_b64_tr_b16 v[60:61], v180 offset:33792
	ds_read_b64_tr_b16 v[62:63], v180 offset:34304
	ds_read_b64_tr_b16 v[64:65], v180 offset:37888
	ds_read_b64_tr_b16 v[66:67], v180 offset:38400
	s_waitcnt lgkmcnt(2)
	v_mfma_f32_32x32x16_bf16 v[16:31], v[60:63], v[68:71], v[16:31]
	s_waitcnt lgkmcnt(0)
	v_mfma_f32_32x32x16_bf16 v[0:15], v[64:67], v[68:71], v[0:15]
	ds_read_b64_tr_b16 v[60:61], v180 offset:34816
	ds_read_b64_tr_b16 v[62:63], v180 offset:35328
	ds_read_b64_tr_b16 v[64:65], v180 offset:38912
	ds_read_b64_tr_b16 v[66:67], v180 offset:39424
	s_waitcnt lgkmcnt(2)
	v_mfma_f32_32x32x16_bf16 v[16:31], v[60:63], v[48:51], v[16:31]
	s_waitcnt lgkmcnt(0)
	v_mfma_f32_32x32x16_bf16 v[0:15], v[64:67], v[48:51], v[0:15]
	ds_read_b64_tr_b16 v[48:49], v180 offset:35840
	ds_read_b64_tr_b16 v[50:51], v180 offset:36352
	ds_read_b64_tr_b16 v[60:61], v180 offset:39936
	ds_read_b64_tr_b16 v[62:63], v180 offset:40448
	s_waitcnt lgkmcnt(2)
	v_mfma_f32_32x32x16_bf16 v[16:31], v[48:51], v[56:59], v[16:31]
	s_waitcnt lgkmcnt(0)
	v_mfma_f32_32x32x16_bf16 v[0:15], v[60:63], v[56:59], v[0:15]
	v_add_f32_e32 v182, v52, v53
	v_add_f32_e32 v183, v54, v55
	v_add_f32_e32 v182, v182, v183
	v_add_f32_e32 v169, v169, v182
	s_waitcnt vmcnt(0)
	s_waitcnt lgkmcnt(0)
	s_barrier
; #define LAS __attribute__((address_space(3)))
; __device__ __forceinline__ void attn_unit(LAS unsigned char* lds, bf16_t* P, const float* qgain, const float* rope, int s, int h, int qb, int lane, int wid, bool dry) {
;     ...
;     *(LAS u32x4*)(lds + kdst) = krA; *(LAS u32x4*)(lds + vdst) = vrA; *(LAS u32x4*)(lds + 8192 + kdst) = krB;
;     asm volatile("s_waitcnt vmcnt(0) lgkmcnt(0)\n\ts_barrier" ::: "memory");
;     krA = *(const u32x4*)(ksrc + (size_t)2 * 64 * EVEN_IN); vrA = *(const u32x4*)(vsrc + (size_t)64 * EVEN_IN);
;     const int koff = hi * 1024 + r32 * 16;
;     const int voff = 16384 + ((lane >> 4) & 1) * 32 + (lane & 3) * 8 + (4 * hi + ((lane & 15) >> 2)) * 64;
	s_add_u32 s84, s84, 0x48000
	s_addc_u32 s85, s85, 0
	s_add_u32 s82, s82, 0x48000
	s_addc_u32 s83, s83, 0
	v_exp_f32_e32 v64, v96
	v_exp_f32_e32 v65, v97
	v_exp_f32_e32 v66, v98
	v_exp_f32_e32 v67, v99
	v_cvt_pk_bf16_f32 v96, v64, v65
	v_cvt_pk_bf16_f32 v97, v66, v67
	v_exp_f32_e32 v68, v80
	v_exp_f32_e32 v69, v81
	v_exp_f32_e32 v70, v82
	v_exp_f32_e32 v71, v83
	v_cvt_pk_bf16_f32 v80, v68, v69
	v_cvt_pk_bf16_f32 v81, v70, v71
	v_add_f32_e32 v68, v68, v64
	v_add_f32_e32 v69, v69, v65
	v_add_f32_e32 v82, v70, v66
	v_add_f32_e32 v83, v71, v67
	v_exp_f32_e32 v98, v100
	v_exp_f32_e32 v99, v101
	v_exp_f32_e32 v100, v102
	v_exp_f32_e32 v101, v103
	v_add_f32_e32 v102, v98, v68
	v_add_f32_e32 v103, v99, v69
	v_add_f32_e32 v82, v100, v82
	v_add_f32_e32 v83, v101, v83
	v_cvt_pk_bf16_f32 v98, v98, v99
	v_cvt_pk_bf16_f32 v99, v100, v101
	v_exp_f32_e32 v84, v84
	v_exp_f32_e32 v85, v85
	v_exp_f32_e32 v86, v86
	v_exp_f32_e32 v87, v87
	v_add_f32_e32 v100, v84, v102
	v_add_f32_e32 v101, v85, v103
	v_add_f32_e32 v102, v86, v82
	v_add_f32_e32 v103, v87, v83
	v_cvt_pk_bf16_f32 v82, v84, v85
	v_cvt_pk_bf16_f32 v83, v86, v87
	v_exp_f32_e32 v84, v104
	v_exp_f32_e32 v85, v105
	v_exp_f32_e32 v86, v106
	v_exp_f32_e32 v87, v107
	v_add_f32_e32 v104, v84, v100
	v_add_f32_e32 v105, v85, v101
	v_add_f32_e32 v102, v86, v102
	v_add_f32_e32 v103, v87, v103
	v_cvt_pk_bf16_f32 v100, v84, v85
	v_cvt_pk_bf16_f32 v101, v86, v87
	v_exp_f32_e32 v84, v88
	v_exp_f32_e32 v85, v89
	v_exp_f32_e32 v86, v90
	v_exp_f32_e32 v87, v91
	v_add_f32_e32 v90, v84, v104
	v_add_f32_e32 v91, v85, v105
	v_add_f32_e32 v102, v86, v102
	v_add_f32_e32 v103, v87, v103
	v_cvt_pk_bf16_f32 v88, v84, v85
	v_cvt_pk_bf16_f32 v89, v86, v87
	v_exp_f32_e32 v84, v108
	v_exp_f32_e32 v85, v109
	v_exp_f32_e32 v86, v110
	v_exp_f32_e32 v87, v111
	v_add_f32_e32 v90, v84, v90
	v_add_f32_e32 v91, v85, v91
	v_add_f32_e32 v104, v86, v102
	v_add_f32_e32 v105, v87, v103
	v_cvt_pk_bf16_f32 v102, v84, v85
	v_cvt_pk_bf16_f32 v103, v86, v87
	v_exp_f32_e32 v92, v92
	v_exp_f32_e32 v93, v93
	v_exp_f32_e32 v94, v94
	v_exp_f32_e32 v95, v95
	v_add_f32_e32 v84, v92, v90
	v_add_f32_e32 v85, v93, v91
	v_add_f32_e32 v86, v94, v104
	v_add_f32_e32 v87, v95, v105
	v_cvt_pk_bf16_f32 v90, v92, v93
	v_cvt_pk_bf16_f32 v91, v94, v95
	ds_read_b64_tr_b16 v[92:93], v180 offset:40960
	ds_read_b64_tr_b16 v[94:95], v180 offset:41472
	ds_read_b64_tr_b16 v[104:105], v180 offset:45056
	ds_read_b64_tr_b16 v[106:107], v180 offset:45568
	s_waitcnt lgkmcnt(2)
	v_mfma_f32_32x32x16_bf16 v[16:31], v[92:95], v[96:99], v[16:31]
	s_waitcnt lgkmcnt(0)
	v_mfma_f32_32x32x16_bf16 v[0:15], v[104:107], v[96:99], v[0:15]
	ds_read_b64_tr_b16 v[92:93], v180 offset:41984
	ds_read_b64_tr_b16 v[94:95], v180 offset:42496
	ds_read_b64_tr_b16 v[96:97], v180 offset:46080
	ds_read_b64_tr_b16 v[98:99], v180 offset:46592
	s_waitcnt lgkmcnt(2)
	v_mfma_f32_32x32x16_bf16 v[16:31], v[92:95], v[100:103], v[16:31]
	s_waitcnt lgkmcnt(0)
	v_mfma_f32_32x32x16_bf16 v[0:15], v[96:99], v[100:103], v[0:15]
	ds_read_b64_tr_b16 v[92:93], v180 offset:43008
	ds_read_b64_tr_b16 v[94:95], v180 offset:43520
	ds_read_b64_tr_b16 v[96:97], v180 offset:47104
	ds_read_b64_tr_b16 v[98:99], v180 offset:47616
	s_waitcnt lgkmcnt(2)
	v_mfma_f32_32x32x16_bf16 v[16:31], v[92:95], v[80:83], v[16:31]
	s_waitcnt lgkmcnt(0)
	v_mfma_f32_32x32x16_bf16 v[0:15], v[96:99], v[80:83], v[0:15]
	ds_read_b64_tr_b16 v[80:81], v180 offset:44032
	ds_read_b64_tr_b16 v[82:83], v180 offset:44544
	ds_read_b64_tr_b16 v[92:93], v180 offset:48128
	ds_read_b64_tr_b16 v[94:95], v180 offset:48640
	s_waitcnt lgkmcnt(2)
	v_mfma_f32_32x32x16_bf16 v[16:31], v[80:83], v[88:91], v[16:31]
	s_waitcnt lgkmcnt(0)
	v_mfma_f32_32x32x16_bf16 v[0:15], v[92:95], v[88:91], v[0:15]
	v_add_f32_e32 v182, v84, v85
	v_add_f32_e32 v183, v86, v87
	v_add_f32_e32 v182, v182, v183
	v_add_f32_e32 v169, v169, v182
	s_waitcnt lgkmcnt(0)
	s_barrier
	s_branch .LBB0_62
.Lfa_g1_entry:
	v_lshl_add_u64 v[146:147], v[174:175], 0, s[46:47]
	v_lshl_add_u64 v[148:149], v[172:173], 0, s[46:47]
	s_nop 0
	v_readfirstlane_b32 s84, v146
	v_readfirstlane_b32 s85, v147
	v_readfirstlane_b32 s82, v148
	v_readfirstlane_b32 s83, v149
	s_nop 3
	v_subrev_u32_e32 v174, s84, v146
	v_subrev_u32_e32 v172, s82, v148
	s_add_u32 s84, s84, 0x88d8c00
	s_addc_u32 s85, s85, 0
	s_add_u32 s82, s82, 0x8890d00
	s_addc_u32 s83, s83, 0
	s_nop 4
	s_lshl_b32 s40, s38, 10
	s_lshr_b32 s41, s38, 2
	s_lshl_b32 s41, s41, 12
	s_and_b32 s39, s38, 3
	s_lshl_b32 s39, s39, 10
	s_add_i32 s41, s41, s39
	s_add_i32 s41, s41, 16384
	s_waitcnt vmcnt(0)
	s_lshl_b32 s39, s38, 4
	s_sub_u32 s84, s84, s39
	s_subb_u32 s85, s85, 0
	v_lshrrev_b32_e32 v142, 3, v198
	v_lshl_add_u32 v142, s38, 3, v142
	v_bfe_u32 v143, v142, 1, 3
	v_and_b32_e32 v144, 7, v198
	v_xor_b32_e32 v143, v143, v144
	v_mul_u32_u24_e32 v174, 0x1200, v142
	v_lshl_add_u32 v174, v143, 4, v174
	v_and_b32_e32 v142, 31, v198
	v_lshrrev_b32_e32 v143, 5, v198
	v_bfe_u32 v144, v142, 1, 3
	v_lshlrev_b32_e32 v142, 7, v142
	v_or_b32_e32 v145, 0, v143
	v_xor_b32_e32 v145, v145, v144
	v_lshl_add_u32 v114, v145, 4, v142
	v_or_b32_e32 v145, 2, v143
	v_xor_b32_e32 v145, v145, v144
	v_lshl_add_u32 v115, v145, 4, v142
	v_or_b32_e32 v145, 4, v143
	v_xor_b32_e32 v145, v145, v144
	v_lshl_add_u32 v116, v145, 4, v142
	v_or_b32_e32 v145, 6, v143
	v_xor_b32_e32 v145, v145, v144
	v_lshl_add_u32 v117, v145, 4, v142
	s_sub_u32 s22, s84, 0x90000
	s_subb_u32 s23, s85, 0
	s_add_i32 m0, s40, 8192
	s_nop 0
	global_load_lds_dwordx4 v174, s[22:23]
	s_add_u32 s22, s22, 0x48000
	s_addc_u32 s23, s23, 0
	s_add_i32 m0, s40, 49152
	s_nop 0
	global_load_lds_dwordx4 v174, s[22:23]
	ds_write_b128 v178, v[138:141] offset:24576
	s_waitcnt vmcnt(0) lgkmcnt(0)
	s_barrier
	s_add_i32 m0, s40, 57344
	s_nop 0
	global_load_lds_dwordx4 v174, s[84:85]
	s_add_i32 m0, s41, 16384
	s_nop 0
	global_load_lds_dwordx4 v172, s[82:83]
	s_add_u32 s84, s84, 0x48000
	s_addc_u32 s85, s85, 0
	s_add_u32 s82, s82, 0x48000
	s_addc_u32 s83, s83, 0
	ds_read_b128 v[80:83], v114 offset:8192
	ds_read_b128 v[182:185], v114 offset:12288
	ds_read_b128 v[186:189], v115 offset:8192
	ds_read_b128 v[190:193], v115 offset:12288
	ds_read_b128 v[200:203], v116 offset:8192
	ds_read_b128 v[204:207], v116 offset:12288
	ds_read_b128 v[208:211], v117 offset:8192
	ds_read_b128 v[212:215], v117 offset:12288
	v_exp_f32_e32 v64, v64
	v_exp_f32_e32 v65, v65
	v_exp_f32_e32 v66, v66
	v_exp_f32_e32 v67, v67
	v_exp_f32_e32 v48, v48
	v_exp_f32_e32 v49, v49
	v_exp_f32_e32 v50, v50
	v_exp_f32_e32 v51, v51
	v_add_f32_e32 v84, v50, v66
	v_add_f32_e32 v85, v51, v67
	v_add_f32_e32 v86, v48, v64
	v_add_f32_e32 v87, v49, v65
	v_cvt_pk_bf16_f32 v64, v64, v65
	v_cvt_pk_bf16_f32 v65, v66, v67
	v_cvt_pk_bf16_f32 v48, v48, v49
	v_cvt_pk_bf16_f32 v49, v50, v51
	s_waitcnt lgkmcnt(7)
	v_mfma_f32_32x32x16_bf16 v[96:111], v[80:83], v[118:121], v[32:47]
	v_exp_f32_e32 v50, v68
	v_exp_f32_e32 v51, v69
	v_exp_f32_e32 v68, v70
	v_exp_f32_e32 v69, v71
	v_add_f32_e32 v70, v50, v86
	v_add_f32_e32 v71, v51, v87
	v_add_f32_e32 v181, v68, v84
	v_add_f32_e32 v228, v69, v85
	v_cvt_pk_bf16_f32 v66, v50, v51
	v_cvt_pk_bf16_f32 v67, v68, v69
	s_waitcnt lgkmcnt(6)
	v_mfma_f32_32x32x16_bf16 v[80:95], v[182:185], v[118:121], v[32:47]
	v_exp_f32_e32 v50, v52
	v_exp_f32_e32 v51, v53
	v_exp_f32_e32 v52, v54
	v_exp_f32_e32 v53, v55
	v_add_f32_e32 v54, v50, v70
	v_add_f32_e32 v55, v51, v71
	v_add_f32_e32 v68, v52, v181
	v_add_f32_e32 v69, v53, v228
	v_cvt_pk_bf16_f32 v50, v50, v51
	v_cvt_pk_bf16_f32 v51, v52, v53
	s_waitcnt lgkmcnt(5)
	v_mfma_f32_32x32x16_bf16 v[96:111], v[186:189], v[122:125], v[96:111]
	v_exp_f32_e32 v52, v72
	v_exp_f32_e32 v53, v73
	v_exp_f32_e32 v70, v74
	v_exp_f32_e32 v71, v75
	v_add_f32_e32 v54, v52, v54
	v_add_f32_e32 v55, v53, v55
	v_add_f32_e32 v72, v70, v68
	v_add_f32_e32 v73, v71, v69
	v_cvt_pk_bf16_f32 v68, v52, v53
	v_cvt_pk_bf16_f32 v69, v70, v71
	s_waitcnt lgkmcnt(4)
	v_mfma_f32_32x32x16_bf16 v[80:95], v[190:193], v[122:125], v[80:95]
	v_exp_f32_e32 v52, v56
	v_exp_f32_e32 v53, v57
	v_exp_f32_e32 v57, v58
	v_exp_f32_e32 v58, v59
	v_add_f32_e32 v54, v52, v54
	v_add_f32_e32 v55, v53, v55
	v_add_f32_e32 v59, v57, v72
	v_add_f32_e32 v70, v58, v73
	v_cvt_pk_bf16_f32 v56, v52, v53
	v_cvt_pk_bf16_f32 v57, v57, v58
	s_waitcnt lgkmcnt(3)
	v_mfma_f32_32x32x16_bf16 v[96:111], v[200:203], v[126:129], v[96:111]
	v_exp_f32_e32 v52, v76
	v_exp_f32_e32 v53, v77
	v_exp_f32_e32 v58, v78
	v_exp_f32_e32 v71, v79
	v_add_f32_e32 v54, v52, v54
	v_add_f32_e32 v55, v53, v55
	v_add_f32_e32 v59, v58, v59
	v_add_f32_e32 v72, v71, v70
	v_cvt_pk_bf16_f32 v70, v52, v53
	v_cvt_pk_bf16_f32 v71, v58, v71
	s_waitcnt lgkmcnt(2)
	v_mfma_f32_32x32x16_bf16 v[80:95], v[204:207], v[126:129], v[80:95]
	v_exp_f32_e32 v58, v60
	v_exp_f32_e32 v60, v61
	v_exp_f32_e32 v61, v62
	v_exp_f32_e32 v62, v63
	v_add_f32_e32 v52, v58, v54
	v_add_f32_e32 v53, v60, v55
	v_add_f32_e32 v54, v61, v59
	v_add_f32_e32 v55, v62, v72
	v_cvt_pk_bf16_f32 v58, v58, v60
	v_cvt_pk_bf16_f32 v59, v61, v62
	s_waitcnt lgkmcnt(1)
	v_mfma_f32_32x32x16_bf16 v[96:111], v[208:211], v[130:133], v[96:111]
	s_waitcnt lgkmcnt(0)
	v_mfma_f32_32x32x16_bf16 v[80:95], v[212:215], v[130:133], v[80:95]
	v_add_f32_e32 v182, v52, v53
	v_add_f32_e32 v183, v54, v55
	v_add_f32_e32 v182, v182, v183
	v_add_f32_e32 v169, v169, v182
	s_waitcnt vmcnt(2)
	s_waitcnt lgkmcnt(0)
	s_barrier
	s_add_i32 m0, s40, 0
	s_nop 0
	global_load_lds_dwordx4 v174, s[84:85]
	s_add_i32 m0, s41, 24576
	s_nop 0
	global_load_lds_dwordx4 v172, s[82:83]
	s_add_u32 s84, s84, 0x48000
	s_addc_u32 s85, s85, 0
	s_add_u32 s82, s82, 0x48000
	s_addc_u32 s83, s83, 0
	ds_read_b64_tr_b16 v[60:61], v180 offset:16384
	ds_read_b64_tr_b16 v[62:63], v180 offset:16896
	ds_read_b64_tr_b16 v[72:73], v180 offset:20480
	ds_read_b64_tr_b16 v[74:75], v180 offset:20992
	s_waitcnt lgkmcnt(2)
	v_mfma_f32_32x32x16_bf16 v[16:31], v[60:63], v[64:67], v[16:31]
	s_waitcnt lgkmcnt(0)
	v_mfma_f32_32x32x16_bf16 v[0:15], v[72:75], v[64:67], v[0:15]
	ds_read_b64_tr_b16 v[60:61], v180 offset:17408
	ds_read_b64_tr_b16 v[62:63], v180 offset:17920
	ds_read_b64_tr_b16 v[64:65], v180 offset:21504
	ds_read_b64_tr_b16 v[66:67], v180 offset:22016
	s_waitcnt lgkmcnt(2)
	v_mfma_f32_32x32x16_bf16 v[16:31], v[60:63], v[68:71], v[16:31]
	s_waitcnt lgkmcnt(0)
	v_mfma_f32_32x32x16_bf16 v[0:15], v[64:67], v[68:71], v[0:15]
	ds_read_b64_tr_b16 v[60:61], v180 offset:18432
	ds_read_b64_tr_b16 v[62:63], v180 offset:18944
	ds_read_b64_tr_b16 v[64:65], v180 offset:22528
	ds_read_b64_tr_b16 v[66:67], v180 offset:23040
	s_waitcnt lgkmcnt(2)
	v_mfma_f32_32x32x16_bf16 v[16:31], v[60:63], v[48:51], v[16:31]
	s_waitcnt lgkmcnt(0)
	v_mfma_f32_32x32x16_bf16 v[0:15], v[64:67], v[48:51], v[0:15]
	ds_read_b64_tr_b16 v[48:49], v180 offset:19456
	ds_read_b64_tr_b16 v[50:51], v180 offset:19968
	ds_read_b64_tr_b16 v[60:61], v180 offset:23552
	ds_read_b64_tr_b16 v[62:63], v180 offset:24064
	s_waitcnt lgkmcnt(2)
	v_mfma_f32_32x32x16_bf16 v[16:31], v[48:51], v[56:59], v[16:31]
	s_waitcnt lgkmcnt(0)
	v_mfma_f32_32x32x16_bf16 v[0:15], v[60:63], v[56:59], v[0:15]
	ds_read_b128 v[182:185], v114 offset:49152
	ds_read_b128 v[186:189], v114 offset:53248
	ds_read_b128 v[190:193], v115 offset:49152
	ds_read_b128 v[200:203], v115 offset:53248
	ds_read_b128 v[204:207], v116 offset:49152
	ds_read_b128 v[208:211], v116 offset:53248
	ds_read_b128 v[212:215], v117 offset:49152
	ds_read_b128 v[146:149], v117 offset:53248
	v_exp_f32_e32 v64, v96
	v_exp_f32_e32 v65, v97
	v_exp_f32_e32 v66, v98
	v_exp_f32_e32 v67, v99
	v_cvt_pk_bf16_f32 v96, v64, v65
	v_cvt_pk_bf16_f32 v97, v66, v67
	v_exp_f32_e32 v68, v80
	v_exp_f32_e32 v69, v81
	v_exp_f32_e32 v70, v82
	v_exp_f32_e32 v71, v83
	v_cvt_pk_bf16_f32 v80, v68, v69
	v_cvt_pk_bf16_f32 v81, v70, v71
	v_add_f32_e32 v68, v68, v64
	v_add_f32_e32 v69, v69, v65
	v_add_f32_e32 v82, v70, v66
	v_add_f32_e32 v83, v71, v67
	v_exp_f32_e32 v98, v100
	v_exp_f32_e32 v99, v101
	v_exp_f32_e32 v100, v102
	v_exp_f32_e32 v101, v103
	v_add_f32_e32 v102, v98, v68
	v_add_f32_e32 v103, v99, v69
	s_waitcnt lgkmcnt(7)
	v_mfma_f32_32x32x16_bf16 v[64:79], v[182:185], v[118:121], v[32:47]
	v_add_f32_e32 v82, v100, v82
	v_add_f32_e32 v83, v101, v83
	v_cvt_pk_bf16_f32 v98, v98, v99
	v_cvt_pk_bf16_f32 v99, v100, v101
	s_waitcnt lgkmcnt(6)
	v_mfma_f32_32x32x16_bf16 v[48:63], v[186:189], v[118:121], v[32:47]
	v_exp_f32_e32 v84, v84
	v_exp_f32_e32 v85, v85
	v_exp_f32_e32 v86, v86
	v_exp_f32_e32 v87, v87
	v_add_f32_e32 v100, v84, v102
	v_add_f32_e32 v101, v85, v103
	v_add_f32_e32 v102, v86, v82
	v_add_f32_e32 v103, v87, v83
	v_cvt_pk_bf16_f32 v82, v84, v85
	v_cvt_pk_bf16_f32 v83, v86, v87
	s_waitcnt lgkmcnt(5)
	v_mfma_f32_32x32x16_bf16 v[64:79], v[190:193], v[122:125], v[64:79]
	v_exp_f32_e32 v84, v104
	v_exp_f32_e32 v85, v105
	v_exp_f32_e32 v86, v106
	v_exp_f32_e32 v87, v107
	v_add_f32_e32 v104, v84, v100
	v_add_f32_e32 v105, v85, v101
	v_add_f32_e32 v102, v86, v102
	v_add_f32_e32 v103, v87, v103
	v_cvt_pk_bf16_f32 v100, v84, v85
	v_cvt_pk_bf16_f32 v101, v86, v87
	s_waitcnt lgkmcnt(4)
	v_mfma_f32_32x32x16_bf16 v[48:63], v[200:203], v[122:125], v[48:63]
	v_exp_f32_e32 v84, v88
	v_exp_f32_e32 v85, v89
	v_exp_f32_e32 v86, v90
	v_exp_f32_e32 v87, v91
	v_add_f32_e32 v90, v84, v104
	v_add_f32_e32 v91, v85, v105
	v_add_f32_e32 v102, v86, v102
	v_add_f32_e32 v103, v87, v103
	v_cvt_pk_bf16_f32 v88, v84, v85
	v_cvt_pk_bf16_f32 v89, v86, v87
	s_waitcnt lgkmcnt(3)
	v_mfma_f32_32x32x16_bf16 v[64:79], v[204:207], v[126:129], v[64:79]
	v_exp_f32_e32 v84, v108
	v_exp_f32_e32 v85, v109
	v_exp_f32_e32 v86, v110
	v_exp_f32_e32 v87, v111
	v_add_f32_e32 v90, v84, v90
	v_add_f32_e32 v91, v85, v91
	v_add_f32_e32 v104, v86, v102
	v_add_f32_e32 v105, v87, v103
	v_cvt_pk_bf16_f32 v102, v84, v85
	v_cvt_pk_bf16_f32 v103, v86, v87
	s_waitcnt lgkmcnt(2)
	v_mfma_f32_32x32x16_bf16 v[48:63], v[208:211], v[126:129], v[48:63]
	v_exp_f32_e32 v92, v92
	v_exp_f32_e32 v93, v93
	v_exp_f32_e32 v94, v94
	v_exp_f32_e32 v95, v95
	v_add_f32_e32 v84, v92, v90
	v_add_f32_e32 v85, v93, v91
	v_add_f32_e32 v86, v94, v104
	v_add_f32_e32 v87, v95, v105
	v_cvt_pk_bf16_f32 v90, v92, v93
	v_cvt_pk_bf16_f32 v91, v94, v95
	s_waitcnt lgkmcnt(1)
	v_mfma_f32_32x32x16_bf16 v[64:79], v[212:215], v[130:133], v[64:79]
	s_waitcnt lgkmcnt(0)
	v_mfma_f32_32x32x16_bf16 v[48:63], v[146:149], v[130:133], v[48:63]
	v_add_f32_e32 v182, v84, v85
	v_add_f32_e32 v183, v86, v87
	v_add_f32_e32 v182, v182, v183
	v_add_f32_e32 v169, v169, v182
	s_waitcnt vmcnt(2)
	s_waitcnt lgkmcnt(0)
	s_barrier
	s_add_i32 m0, s40, 8192
	s_nop 0
	global_load_lds_dwordx4 v174, s[84:85]
	s_add_i32 m0, s41, 0
	s_nop 0
	global_load_lds_dwordx4 v172, s[82:83]
	s_add_u32 s84, s84, 0x48000
	s_addc_u32 s85, s85, 0
	s_add_u32 s82, s82, 0x48000
	s_addc_u32 s83, s83, 0
	ds_read_b64_tr_b16 v[92:93], v180 offset:24576
	ds_read_b64_tr_b16 v[94:95], v180 offset:25088
	ds_read_b64_tr_b16 v[104:105], v180 offset:28672
	ds_read_b64_tr_b16 v[106:107], v180 offset:29184
	s_waitcnt lgkmcnt(2)
	v_mfma_f32_32x32x16_bf16 v[16:31], v[92:95], v[96:99], v[16:31]
	s_waitcnt lgkmcnt(0)
	v_mfma_f32_32x32x16_bf16 v[0:15], v[104:107], v[96:99], v[0:15]
	ds_read_b64_tr_b16 v[92:93], v180 offset:25600
	ds_read_b64_tr_b16 v[94:95], v180 offset:26112
	ds_read_b64_tr_b16 v[96:97], v180 offset:29696
	ds_read_b64_tr_b16 v[98:99], v180 offset:30208
	s_waitcnt lgkmcnt(2)
	v_mfma_f32_32x32x16_bf16 v[16:31], v[92:95], v[100:103], v[16:31]
	s_waitcnt lgkmcnt(0)
	v_mfma_f32_32x32x16_bf16 v[0:15], v[96:99], v[100:103], v[0:15]
	ds_read_b64_tr_b16 v[92:93], v180 offset:26624
	ds_read_b64_tr_b16 v[94:95], v180 offset:27136
	ds_read_b64_tr_b16 v[96:97], v180 offset:30720
	ds_read_b64_tr_b16 v[98:99], v180 offset:31232
	s_waitcnt lgkmcnt(2)
	v_mfma_f32_32x32x16_bf16 v[16:31], v[92:95], v[80:83], v[16:31]
	s_waitcnt lgkmcnt(0)
	v_mfma_f32_32x32x16_bf16 v[0:15], v[96:99], v[80:83], v[0:15]
	ds_read_b64_tr_b16 v[80:81], v180 offset:27648
	ds_read_b64_tr_b16 v[82:83], v180 offset:28160
	ds_read_b64_tr_b16 v[92:93], v180 offset:31744
	ds_read_b64_tr_b16 v[94:95], v180 offset:32256
	s_waitcnt lgkmcnt(2)
	v_mfma_f32_32x32x16_bf16 v[16:31], v[80:83], v[88:91], v[16:31]
	s_waitcnt lgkmcnt(0)
	v_mfma_f32_32x32x16_bf16 v[0:15], v[92:95], v[88:91], v[0:15]
	ds_read_b128 v[80:83], v114 offset:57344
	ds_read_b128 v[182:185], v114 offset:61440
	ds_read_b128 v[186:189], v115 offset:57344
	ds_read_b128 v[190:193], v115 offset:61440
	ds_read_b128 v[200:203], v116 offset:57344
	ds_read_b128 v[204:207], v116 offset:61440
	ds_read_b128 v[208:211], v117 offset:57344
	ds_read_b128 v[212:215], v117 offset:61440
	v_exp_f32_e32 v64, v64
	v_exp_f32_e32 v65, v65
	v_exp_f32_e32 v66, v66
	v_exp_f32_e32 v67, v67
	v_exp_f32_e32 v48, v48
	v_exp_f32_e32 v49, v49
	v_exp_f32_e32 v50, v50
	v_exp_f32_e32 v51, v51
	v_add_f32_e32 v84, v50, v66
	v_add_f32_e32 v85, v51, v67
	v_add_f32_e32 v86, v48, v64
	v_add_f32_e32 v87, v49, v65
	v_cvt_pk_bf16_f32 v64, v64, v65
	v_cvt_pk_bf16_f32 v65, v66, v67
	v_cvt_pk_bf16_f32 v48, v48, v49
	v_cvt_pk_bf16_f32 v49, v50, v51
	s_waitcnt lgkmcnt(7)
	v_mfma_f32_32x32x16_bf16 v[96:111], v[80:83], v[118:121], v[32:47]
	v_exp_f32_e32 v50, v68
	v_exp_f32_e32 v51, v69
	v_exp_f32_e32 v68, v70
	v_exp_f32_e32 v69, v71
	v_add_f32_e32 v70, v50, v86
	v_add_f32_e32 v71, v51, v87
	v_add_f32_e32 v181, v68, v84
	v_add_f32_e32 v228, v69, v85
	v_cvt_pk_bf16_f32 v66, v50, v51
	v_cvt_pk_bf16_f32 v67, v68, v69
	s_waitcnt lgkmcnt(6)
	v_mfma_f32_32x32x16_bf16 v[80:95], v[182:185], v[118:121], v[32:47]
	v_exp_f32_e32 v50, v52
	v_exp_f32_e32 v51, v53
	v_exp_f32_e32 v52, v54
	v_exp_f32_e32 v53, v55
	v_add_f32_e32 v54, v50, v70
	v_add_f32_e32 v55, v51, v71
	v_add_f32_e32 v68, v52, v181
	v_add_f32_e32 v69, v53, v228
	v_cvt_pk_bf16_f32 v50, v50, v51
	v_cvt_pk_bf16_f32 v51, v52, v53
	s_waitcnt lgkmcnt(5)
	v_mfma_f32_32x32x16_bf16 v[96:111], v[186:189], v[122:125], v[96:111]
	v_exp_f32_e32 v52, v72
	v_exp_f32_e32 v53, v73
	v_exp_f32_e32 v70, v74
	v_exp_f32_e32 v71, v75
	v_add_f32_e32 v54, v52, v54
	v_add_f32_e32 v55, v53, v55
	v_add_f32_e32 v72, v70, v68
	v_add_f32_e32 v73, v71, v69
	v_cvt_pk_bf16_f32 v68, v52, v53
	v_cvt_pk_bf16_f32 v69, v70, v71
	s_waitcnt lgkmcnt(4)
	v_mfma_f32_32x32x16_bf16 v[80:95], v[190:193], v[122:125], v[80:95]
	v_exp_f32_e32 v52, v56
	v_exp_f32_e32 v53, v57
	v_exp_f32_e32 v57, v58
	v_exp_f32_e32 v58, v59
	v_add_f32_e32 v54, v52, v54
	v_add_f32_e32 v55, v53, v55
	v_add_f32_e32 v59, v57, v72
	v_add_f32_e32 v70, v58, v73
	v_cvt_pk_bf16_f32 v56, v52, v53
	v_cvt_pk_bf16_f32 v57, v57, v58
	s_waitcnt lgkmcnt(3)
	v_mfma_f32_32x32x16_bf16 v[96:111], v[200:203], v[126:129], v[96:111]
	v_exp_f32_e32 v52, v76
	v_exp_f32_e32 v53, v77
	v_exp_f32_e32 v58, v78
	v_exp_f32_e32 v71, v79
	v_add_f32_e32 v54, v52, v54
	v_add_f32_e32 v55, v53, v55
	v_add_f32_e32 v59, v58, v59
	v_add_f32_e32 v72, v71, v70
	v_cvt_pk_bf16_f32 v70, v52, v53
	v_cvt_pk_bf16_f32 v71, v58, v71
	s_waitcnt lgkmcnt(2)
	v_mfma_f32_32x32x16_bf16 v[80:95], v[204:207], v[126:129], v[80:95]
	v_exp_f32_e32 v58, v60
	v_exp_f32_e32 v60, v61
	v_exp_f32_e32 v61, v62
	v_exp_f32_e32 v62, v63
	v_add_f32_e32 v52, v58, v54
	v_add_f32_e32 v53, v60, v55
	v_add_f32_e32 v54, v61, v59
	v_add_f32_e32 v55, v62, v72
	v_cvt_pk_bf16_f32 v58, v58, v60
	v_cvt_pk_bf16_f32 v59, v61, v62
	s_waitcnt lgkmcnt(1)
	v_mfma_f32_32x32x16_bf16 v[96:111], v[208:211], v[130:133], v[96:111]
	s_waitcnt lgkmcnt(0)
	v_mfma_f32_32x32x16_bf16 v[80:95], v[212:215], v[130:133], v[80:95]
	v_add_f32_e32 v182, v52, v53
	v_add_f32_e32 v183, v54, v55
	v_add_f32_e32 v182, v182, v183
	v_add_f32_e32 v169, v169, v182
	s_waitcnt vmcnt(2)
	s_waitcnt lgkmcnt(0)
	s_barrier
	s_add_i32 m0, s40, 49152
	s_nop 0
	global_load_lds_dwordx4 v174, s[84:85]
	s_add_i32 m0, s41, 8192
	s_nop 0
	global_load_lds_dwordx4 v172, s[82:83]
	s_add_u32 s84, s84, 0x48000
	s_addc_u32 s85, s85, 0
	s_add_u32 s82, s82, 0x48000
	s_addc_u32 s83, s83, 0
	ds_read_b64_tr_b16 v[60:61], v180 offset:32768
	ds_read_b64_tr_b16 v[62:63], v180 offset:33280
	ds_read_b64_tr_b16 v[72:73], v180 offset:36864
	ds_read_b64_tr_b16 v[74:75], v180 offset:37376
	s_waitcnt lgkmcnt(2)
	v_mfma_f32_32x32x16_bf16 v[16:31], v[60:63], v[64:67], v[16:31]
	s_waitcnt lgkmcnt(0)
	v_mfma_f32_32x32x16_bf16 v[0:15], v[72:75], v[64:67], v[0:15]
	ds_read_b64_tr_b16 v[60:61], v180 offset:33792
	ds_read_b64_tr_b16 v[62:63], v180 offset:34304
	ds_read_b64_tr_b16 v[64:65], v180 offset:37888
	ds_read_b64_tr_b16 v[66:67], v180 offset:38400
	s_waitcnt lgkmcnt(2)
	v_mfma_f32_32x32x16_bf16 v[16:31], v[60:63], v[68:71], v[16:31]
	s_waitcnt lgkmcnt(0)
	v_mfma_f32_32x32x16_bf16 v[0:15], v[64:67], v[68:71], v[0:15]
	ds_read_b64_tr_b16 v[60:61], v180 offset:34816
	ds_read_b64_tr_b16 v[62:63], v180 offset:35328
	ds_read_b64_tr_b16 v[64:65], v180 offset:38912
	ds_read_b64_tr_b16 v[66:67], v180 offset:39424
	s_waitcnt lgkmcnt(2)
	v_mfma_f32_32x32x16_bf16 v[16:31], v[60:63], v[48:51], v[16:31]
	s_waitcnt lgkmcnt(0)
	v_mfma_f32_32x32x16_bf16 v[0:15], v[64:67], v[48:51], v[0:15]
	ds_read_b64_tr_b16 v[48:49], v180 offset:35840
	ds_read_b64_tr_b16 v[50:51], v180 offset:36352
	ds_read_b64_tr_b16 v[60:61], v180 offset:39936
	ds_read_b64_tr_b16 v[62:63], v180 offset:40448
	s_waitcnt lgkmcnt(2)
	v_mfma_f32_32x32x16_bf16 v[16:31], v[48:51], v[56:59], v[16:31]
	s_waitcnt lgkmcnt(0)
	v_mfma_f32_32x32x16_bf16 v[0:15], v[60:63], v[56:59], v[0:15]
	ds_read_b128 v[182:185], v114
	ds_read_b128 v[186:189], v114 offset:4096
	ds_read_b128 v[190:193], v115
	ds_read_b128 v[200:203], v115 offset:4096
	ds_read_b128 v[204:207], v116
	ds_read_b128 v[208:211], v116 offset:4096
	ds_read_b128 v[212:215], v117
	ds_read_b128 v[146:149], v117 offset:4096
	v_exp_f32_e32 v64, v96
	v_exp_f32_e32 v65, v97
	v_exp_f32_e32 v66, v98
	v_exp_f32_e32 v67, v99
	v_cvt_pk_bf16_f32 v96, v64, v65
	v_cvt_pk_bf16_f32 v97, v66, v67
	v_exp_f32_e32 v68, v80
	v_exp_f32_e32 v69, v81
	v_exp_f32_e32 v70, v82
	v_exp_f32_e32 v71, v83
	v_cvt_pk_bf16_f32 v80, v68, v69
	v_cvt_pk_bf16_f32 v81, v70, v71
	v_add_f32_e32 v68, v68, v64
	v_add_f32_e32 v69, v69, v65
	v_add_f32_e32 v82, v70, v66
	v_add_f32_e32 v83, v71, v67
	v_exp_f32_e32 v98, v100
	v_exp_f32_e32 v99, v101
	v_exp_f32_e32 v100, v102
	v_exp_f32_e32 v101, v103
	v_add_f32_e32 v102, v98, v68
	v_add_f32_e32 v103, v99, v69
	s_waitcnt lgkmcnt(7)
	v_mfma_f32_32x32x16_bf16 v[64:79], v[182:185], v[118:121], v[32:47]
	v_add_f32_e32 v82, v100, v82
	v_add_f32_e32 v83, v101, v83
	v_cvt_pk_bf16_f32 v98, v98, v99
	v_cvt_pk_bf16_f32 v99, v100, v101
	s_waitcnt lgkmcnt(6)
	v_mfma_f32_32x32x16_bf16 v[48:63], v[186:189], v[118:121], v[32:47]
	v_exp_f32_e32 v84, v84
	v_exp_f32_e32 v85, v85
	v_exp_f32_e32 v86, v86
	v_exp_f32_e32 v87, v87
	v_add_f32_e32 v100, v84, v102
	v_add_f32_e32 v101, v85, v103
	v_add_f32_e32 v102, v86, v82
	v_add_f32_e32 v103, v87, v83
	v_cvt_pk_bf16_f32 v82, v84, v85
	v_cvt_pk_bf16_f32 v83, v86, v87
	s_waitcnt lgkmcnt(5)
	v_mfma_f32_32x32x16_bf16 v[64:79], v[190:193], v[122:125], v[64:79]
	v_exp_f32_e32 v84, v104
	v_exp_f32_e32 v85, v105
	v_exp_f32_e32 v86, v106
	v_exp_f32_e32 v87, v107
	v_add_f32_e32 v104, v84, v100
	v_add_f32_e32 v105, v85, v101
	v_add_f32_e32 v102, v86, v102
	v_add_f32_e32 v103, v87, v103
	v_cvt_pk_bf16_f32 v100, v84, v85
	v_cvt_pk_bf16_f32 v101, v86, v87
	s_waitcnt lgkmcnt(4)
	v_mfma_f32_32x32x16_bf16 v[48:63], v[200:203], v[122:125], v[48:63]
	v_exp_f32_e32 v84, v88
	v_exp_f32_e32 v85, v89
	v_exp_f32_e32 v86, v90
	v_exp_f32_e32 v87, v91
	v_add_f32_e32 v90, v84, v104
	v_add_f32_e32 v91, v85, v105
	v_add_f32_e32 v102, v86, v102
	v_add_f32_e32 v103, v87, v103
	v_cvt_pk_bf16_f32 v88, v84, v85
	v_cvt_pk_bf16_f32 v89, v86, v87
	s_waitcnt lgkmcnt(3)
	v_mfma_f32_32x32x16_bf16 v[64:79], v[204:207], v[126:129], v[64:79]
	v_exp_f32_e32 v84, v108
	v_exp_f32_e32 v85, v109
	v_exp_f32_e32 v86, v110
	v_exp_f32_e32 v87, v111
	v_add_f32_e32 v90, v84, v90
	v_add_f32_e32 v91, v85, v91
	v_add_f32_e32 v104, v86, v102
	v_add_f32_e32 v105, v87, v103
	v_cvt_pk_bf16_f32 v102, v84, v85
	v_cvt_pk_bf16_f32 v103, v86, v87
	s_waitcnt lgkmcnt(2)
	v_mfma_f32_32x32x16_bf16 v[48:63], v[208:211], v[126:129], v[48:63]
	v_exp_f32_e32 v92, v92
	v_exp_f32_e32 v93, v93
	v_exp_f32_e32 v94, v94
	v_exp_f32_e32 v95, v95
	v_add_f32_e32 v84, v92, v90
	v_add_f32_e32 v85, v93, v91
	v_add_f32_e32 v86, v94, v104
	v_add_f32_e32 v87, v95, v105
	v_cvt_pk_bf16_f32 v90, v92, v93
	v_cvt_pk_bf16_f32 v91, v94, v95
	s_waitcnt lgkmcnt(1)
	v_mfma_f32_32x32x16_bf16 v[64:79], v[212:215], v[130:133], v[64:79]
	s_waitcnt lgkmcnt(0)
	v_mfma_f32_32x32x16_bf16 v[48:63], v[146:149], v[130:133], v[48:63]
	v_add_f32_e32 v182, v84, v85
	v_add_f32_e32 v183, v86, v87
	v_add_f32_e32 v182, v182, v183
	v_add_f32_e32 v169, v169, v182
	s_waitcnt vmcnt(2)
	s_waitcnt lgkmcnt(0)
	s_barrier
	s_mov_b32 s80, 4
.Lfa_g1_loop:
	s_add_i32 m0, s40, 57344
	s_nop 0
	global_load_lds_dwordx4 v174, s[84:85]
	s_add_i32 m0, s41, 16384
	s_nop 0
	global_load_lds_dwordx4 v172, s[82:83]
	s_add_u32 s84, s84, 0x48000
	s_addc_u32 s85, s85, 0
	s_add_u32 s82, s82, 0x48000
	s_addc_u32 s83, s83, 0
	ds_read_b64_tr_b16 v[92:93], v180 offset:40960
	ds_read_b64_tr_b16 v[94:95], v180 offset:41472
	ds_read_b64_tr_b16 v[104:105], v180 offset:45056
	ds_read_b64_tr_b16 v[106:107], v180 offset:45568
	s_waitcnt lgkmcnt(2)
	v_mfma_f32_32x32x16_bf16 v[16:31], v[92:95], v[96:99], v[16:31]
	s_waitcnt lgkmcnt(0)
	v_mfma_f32_32x32x16_bf16 v[0:15], v[104:107], v[96:99], v[0:15]
	ds_read_b64_tr_b16 v[92:93], v180 offset:41984
	ds_read_b64_tr_b16 v[94:95], v180 offset:42496
	ds_read_b64_tr_b16 v[96:97], v180 offset:46080
	ds_read_b64_tr_b16 v[98:99], v180 offset:46592
	s_waitcnt lgkmcnt(2)
	v_mfma_f32_32x32x16_bf16 v[16:31], v[92:95], v[100:103], v[16:31]
	s_waitcnt lgkmcnt(0)
	v_mfma_f32_32x32x16_bf16 v[0:15], v[96:99], v[100:103], v[0:15]
	ds_read_b64_tr_b16 v[92:93], v180 offset:43008
	ds_read_b64_tr_b16 v[94:95], v180 offset:43520
	ds_read_b64_tr_b16 v[96:97], v180 offset:47104
	ds_read_b64_tr_b16 v[98:99], v180 offset:47616
	s_waitcnt lgkmcnt(2)
	v_mfma_f32_32x32x16_bf16 v[16:31], v[92:95], v[80:83], v[16:31]
	s_waitcnt lgkmcnt(0)
	v_mfma_f32_32x32x16_bf16 v[0:15], v[96:99], v[80:83], v[0:15]
	ds_read_b64_tr_b16 v[80:81], v180 offset:44032
	ds_read_b64_tr_b16 v[82:83], v180 offset:44544
	ds_read_b64_tr_b16 v[92:93], v180 offset:48128
	ds_read_b64_tr_b16 v[94:95], v180 offset:48640
	s_waitcnt lgkmcnt(2)
	v_mfma_f32_32x32x16_bf16 v[16:31], v[80:83], v[88:91], v[16:31]
	s_waitcnt lgkmcnt(0)
	v_mfma_f32_32x32x16_bf16 v[0:15], v[92:95], v[88:91], v[0:15]
	ds_read_b128 v[80:83], v114 offset:8192
	ds_read_b128 v[182:185], v114 offset:12288
	ds_read_b128 v[186:189], v115 offset:8192
	ds_read_b128 v[190:193], v115 offset:12288
	ds_read_b128 v[200:203], v116 offset:8192
	ds_read_b128 v[204:207], v116 offset:12288
	ds_read_b128 v[208:211], v117 offset:8192
	ds_read_b128 v[212:215], v117 offset:12288
	v_exp_f32_e32 v64, v64
	v_exp_f32_e32 v65, v65
	v_exp_f32_e32 v66, v66
	v_exp_f32_e32 v67, v67
	v_exp_f32_e32 v48, v48
	v_exp_f32_e32 v49, v49
	v_exp_f32_e32 v50, v50
	v_exp_f32_e32 v51, v51
	v_add_f32_e32 v84, v50, v66
	v_add_f32_e32 v85, v51, v67
	v_add_f32_e32 v86, v48, v64
	v_add_f32_e32 v87, v49, v65
	v_cvt_pk_bf16_f32 v64, v64, v65
	v_cvt_pk_bf16_f32 v65, v66, v67
	v_cvt_pk_bf16_f32 v48, v48, v49
	v_cvt_pk_bf16_f32 v49, v50, v51
	s_waitcnt lgkmcnt(7)
	v_mfma_f32_32x32x16_bf16 v[96:111], v[80:83], v[118:121], v[32:47]
	v_exp_f32_e32 v50, v68
	v_exp_f32_e32 v51, v69
	v_exp_f32_e32 v68, v70
	v_exp_f32_e32 v69, v71
	v_add_f32_e32 v70, v50, v86
	v_add_f32_e32 v71, v51, v87
	v_add_f32_e32 v181, v68, v84
	v_add_f32_e32 v228, v69, v85
	v_cvt_pk_bf16_f32 v66, v50, v51
	v_cvt_pk_bf16_f32 v67, v68, v69
	s_waitcnt lgkmcnt(6)
	v_mfma_f32_32x32x16_bf16 v[80:95], v[182:185], v[118:121], v[32:47]
	v_exp_f32_e32 v50, v52
	v_exp_f32_e32 v51, v53
	v_exp_f32_e32 v52, v54
	v_exp_f32_e32 v53, v55
	v_add_f32_e32 v54, v50, v70
	v_add_f32_e32 v55, v51, v71
	v_add_f32_e32 v68, v52, v181
	v_add_f32_e32 v69, v53, v228
	v_cvt_pk_bf16_f32 v50, v50, v51
	v_cvt_pk_bf16_f32 v51, v52, v53
	s_waitcnt lgkmcnt(5)
	v_mfma_f32_32x32x16_bf16 v[96:111], v[186:189], v[122:125], v[96:111]
	v_exp_f32_e32 v52, v72
	v_exp_f32_e32 v53, v73
	v_exp_f32_e32 v70, v74
	v_exp_f32_e32 v71, v75
	v_add_f32_e32 v54, v52, v54
	v_add_f32_e32 v55, v53, v55
	v_add_f32_e32 v72, v70, v68
	v_add_f32_e32 v73, v71, v69
	v_cvt_pk_bf16_f32 v68, v52, v53
	v_cvt_pk_bf16_f32 v69, v70, v71
	s_waitcnt lgkmcnt(4)
	v_mfma_f32_32x32x16_bf16 v[80:95], v[190:193], v[122:125], v[80:95]
	v_exp_f32_e32 v52, v56
	v_exp_f32_e32 v53, v57
	v_exp_f32_e32 v57, v58
	v_exp_f32_e32 v58, v59
	v_add_f32_e32 v54, v52, v54
	v_add_f32_e32 v55, v53, v55
	v_add_f32_e32 v59, v57, v72
	v_add_f32_e32 v70, v58, v73
	v_cvt_pk_bf16_f32 v56, v52, v53
	v_cvt_pk_bf16_f32 v57, v57, v58
	s_waitcnt lgkmcnt(3)
	v_mfma_f32_32x32x16_bf16 v[96:111], v[200:203], v[126:129], v[96:111]
	v_exp_f32_e32 v52, v76
	v_exp_f32_e32 v53, v77
	v_exp_f32_e32 v58, v78
	v_exp_f32_e32 v71, v79
	v_add_f32_e32 v54, v52, v54
	v_add_f32_e32 v55, v53, v55
	v_add_f32_e32 v59, v58, v59
	v_add_f32_e32 v72, v71, v70
	v_cvt_pk_bf16_f32 v70, v52, v53
	v_cvt_pk_bf16_f32 v71, v58, v71
	s_waitcnt lgkmcnt(2)
	v_mfma_f32_32x32x16_bf16 v[80:95], v[204:207], v[126:129], v[80:95]
	v_exp_f32_e32 v58, v60
	v_exp_f32_e32 v60, v61
	v_exp_f32_e32 v61, v62
	v_exp_f32_e32 v62, v63
	v_add_f32_e32 v52, v58, v54
	v_add_f32_e32 v53, v60, v55
	v_add_f32_e32 v54, v61, v59
	v_add_f32_e32 v55, v62, v72
	v_cvt_pk_bf16_f32 v58, v58, v60
	v_cvt_pk_bf16_f32 v59, v61, v62
	s_waitcnt lgkmcnt(1)
	v_mfma_f32_32x32x16_bf16 v[96:111], v[208:211], v[130:133], v[96:111]
	s_waitcnt lgkmcnt(0)
	v_mfma_f32_32x32x16_bf16 v[80:95], v[212:215], v[130:133], v[80:95]
	v_add_f32_e32 v182, v52, v53
	v_add_f32_e32 v183, v54, v55
	v_add_f32_e32 v182, v182, v183
	v_add_f32_e32 v169, v169, v182
	s_waitcnt vmcnt(2)
	s_waitcnt lgkmcnt(0)
	s_barrier
	s_add_i32 m0, s40, 0
	s_nop 0
	global_load_lds_dwordx4 v174, s[84:85]
	s_add_i32 m0, s41, 24576
	s_nop 0
	global_load_lds_dwordx4 v172, s[82:83]
	s_add_u32 s84, s84, 0x48000
	s_addc_u32 s85, s85, 0
	s_add_u32 s82, s82, 0x48000
	s_addc_u32 s83, s83, 0
	ds_read_b64_tr_b16 v[60:61], v180 offset:16384
	ds_read_b64_tr_b16 v[62:63], v180 offset:16896
	ds_read_b64_tr_b16 v[72:73], v180 offset:20480
	ds_read_b64_tr_b16 v[74:75], v180 offset:20992
	s_waitcnt lgkmcnt(2)
	v_mfma_f32_32x32x16_bf16 v[16:31], v[60:63], v[64:67], v[16:31]
	s_waitcnt lgkmcnt(0)
	v_mfma_f32_32x32x16_bf16 v[0:15], v[72:75], v[64:67], v[0:15]
	ds_read_b64_tr_b16 v[60:61], v180 offset:17408
	ds_read_b64_tr_b16 v[62:63], v180 offset:17920
	ds_read_b64_tr_b16 v[64:65], v180 offset:21504
	ds_read_b64_tr_b16 v[66:67], v180 offset:22016
	s_waitcnt lgkmcnt(2)
	v_mfma_f32_32x32x16_bf16 v[16:31], v[60:63], v[68:71], v[16:31]
	s_waitcnt lgkmcnt(0)
	v_mfma_f32_32x32x16_bf16 v[0:15], v[64:67], v[68:71], v[0:15]
	ds_read_b64_tr_b16 v[60:61], v180 offset:18432
	ds_read_b64_tr_b16 v[62:63], v180 offset:18944
	ds_read_b64_tr_b16 v[64:65], v180 offset:22528
	ds_read_b64_tr_b16 v[66:67], v180 offset:23040
	s_waitcnt lgkmcnt(2)
	v_mfma_f32_32x32x16_bf16 v[16:31], v[60:63], v[48:51], v[16:31]
	s_waitcnt lgkmcnt(0)
	v_mfma_f32_32x32x16_bf16 v[0:15], v[64:67], v[48:51], v[0:15]
	ds_read_b64_tr_b16 v[48:49], v180 offset:19456
	ds_read_b64_tr_b16 v[50:51], v180 offset:19968
	ds_read_b64_tr_b16 v[60:61], v180 offset:23552
	ds_read_b64_tr_b16 v[62:63], v180 offset:24064
	s_waitcnt lgkmcnt(2)
	v_mfma_f32_32x32x16_bf16 v[16:31], v[48:51], v[56:59], v[16:31]
	s_waitcnt lgkmcnt(0)
	v_mfma_f32_32x32x16_bf16 v[0:15], v[60:63], v[56:59], v[0:15]
	ds_read_b128 v[182:185], v114 offset:49152
	ds_read_b128 v[186:189], v114 offset:53248
	ds_read_b128 v[190:193], v115 offset:49152
	ds_read_b128 v[200:203], v115 offset:53248
	ds_read_b128 v[204:207], v116 offset:49152
	ds_read_b128 v[208:211], v116 offset:53248
	ds_read_b128 v[212:215], v117 offset:49152
	ds_read_b128 v[146:149], v117 offset:53248
	v_exp_f32_e32 v64, v96
	v_exp_f32_e32 v65, v97
	v_exp_f32_e32 v66, v98
	v_exp_f32_e32 v67, v99
	v_cvt_pk_bf16_f32 v96, v64, v65
	v_cvt_pk_bf16_f32 v97, v66, v67
	v_exp_f32_e32 v68, v80
	v_exp_f32_e32 v69, v81
	v_exp_f32_e32 v70, v82
	v_exp_f32_e32 v71, v83
	v_cvt_pk_bf16_f32 v80, v68, v69
	v_cvt_pk_bf16_f32 v81, v70, v71
	v_add_f32_e32 v68, v68, v64
	v_add_f32_e32 v69, v69, v65
	v_add_f32_e32 v82, v70, v66
	v_add_f32_e32 v83, v71, v67
	v_exp_f32_e32 v98, v100
	v_exp_f32_e32 v99, v101
	v_exp_f32_e32 v100, v102
	v_exp_f32_e32 v101, v103
	v_add_f32_e32 v102, v98, v68
	v_add_f32_e32 v103, v99, v69
	s_waitcnt lgkmcnt(7)
	v_mfma_f32_32x32x16_bf16 v[64:79], v[182:185], v[118:121], v[32:47]
	v_add_f32_e32 v82, v100, v82
	v_add_f32_e32 v83, v101, v83
	v_cvt_pk_bf16_f32 v98, v98, v99
	v_cvt_pk_bf16_f32 v99, v100, v101
	s_waitcnt lgkmcnt(6)
	v_mfma_f32_32x32x16_bf16 v[48:63], v[186:189], v[118:121], v[32:47]
	v_exp_f32_e32 v84, v84
	v_exp_f32_e32 v85, v85
	v_exp_f32_e32 v86, v86
	v_exp_f32_e32 v87, v87
	v_add_f32_e32 v100, v84, v102
	v_add_f32_e32 v101, v85, v103
	v_add_f32_e32 v102, v86, v82
	v_add_f32_e32 v103, v87, v83
	v_cvt_pk_bf16_f32 v82, v84, v85
	v_cvt_pk_bf16_f32 v83, v86, v87
	s_waitcnt lgkmcnt(5)
	v_mfma_f32_32x32x16_bf16 v[64:79], v[190:193], v[122:125], v[64:79]
	v_exp_f32_e32 v84, v104
	v_exp_f32_e32 v85, v105
	v_exp_f32_e32 v86, v106
	v_exp_f32_e32 v87, v107
	v_add_f32_e32 v104, v84, v100
	v_add_f32_e32 v105, v85, v101
	v_add_f32_e32 v102, v86, v102
	v_add_f32_e32 v103, v87, v103
	v_cvt_pk_bf16_f32 v100, v84, v85
	v_cvt_pk_bf16_f32 v101, v86, v87
	s_waitcnt lgkmcnt(4)
	v_mfma_f32_32x32x16_bf16 v[48:63], v[200:203], v[122:125], v[48:63]
	v_exp_f32_e32 v84, v88
	v_exp_f32_e32 v85, v89
	v_exp_f32_e32 v86, v90
	v_exp_f32_e32 v87, v91
	v_add_f32_e32 v90, v84, v104
	v_add_f32_e32 v91, v85, v105
	v_add_f32_e32 v102, v86, v102
	v_add_f32_e32 v103, v87, v103
	v_cvt_pk_bf16_f32 v88, v84, v85
	v_cvt_pk_bf16_f32 v89, v86, v87
	s_waitcnt lgkmcnt(3)
	v_mfma_f32_32x32x16_bf16 v[64:79], v[204:207], v[126:129], v[64:79]
	v_exp_f32_e32 v84, v108
	v_exp_f32_e32 v85, v109
	v_exp_f32_e32 v86, v110
	v_exp_f32_e32 v87, v111
	v_add_f32_e32 v90, v84, v90
	v_add_f32_e32 v91, v85, v91
	v_add_f32_e32 v104, v86, v102
	v_add_f32_e32 v105, v87, v103
	v_cvt_pk_bf16_f32 v102, v84, v85
	v_cvt_pk_bf16_f32 v103, v86, v87
	s_waitcnt lgkmcnt(2)
	v_mfma_f32_32x32x16_bf16 v[48:63], v[208:211], v[126:129], v[48:63]
	v_exp_f32_e32 v92, v92
	v_exp_f32_e32 v93, v93
	v_exp_f32_e32 v94, v94
	v_exp_f32_e32 v95, v95
	v_add_f32_e32 v84, v92, v90
	v_add_f32_e32 v85, v93, v91
	v_add_f32_e32 v86, v94, v104
	v_add_f32_e32 v87, v95, v105
	v_cvt_pk_bf16_f32 v90, v92, v93
	v_cvt_pk_bf16_f32 v91, v94, v95
	s_waitcnt lgkmcnt(1)
	v_mfma_f32_32x32x16_bf16 v[64:79], v[212:215], v[130:133], v[64:79]
	s_waitcnt lgkmcnt(0)
	v_mfma_f32_32x32x16_bf16 v[48:63], v[146:149], v[130:133], v[48:63]
	v_add_f32_e32 v182, v84, v85
	v_add_f32_e32 v183, v86, v87
	v_add_f32_e32 v182, v182, v183
	v_add_f32_e32 v169, v169, v182
	s_waitcnt vmcnt(2)
	s_waitcnt lgkmcnt(0)
	s_barrier
	s_add_i32 m0, s40, 8192
	s_nop 0
	global_load_lds_dwordx4 v174, s[84:85]
	s_add_i32 m0, s41, 0
	s_nop 0
	global_load_lds_dwordx4 v172, s[82:83]
	s_add_u32 s84, s84, 0x48000
	s_addc_u32 s85, s85, 0
	s_add_u32 s82, s82, 0x48000
	s_addc_u32 s83, s83, 0
	ds_read_b64_tr_b16 v[92:93], v180 offset:24576
	ds_read_b64_tr_b16 v[94:95], v180 offset:25088
	ds_read_b64_tr_b16 v[104:105], v180 offset:28672
	ds_read_b64_tr_b16 v[106:107], v180 offset:29184
	s_waitcnt lgkmcnt(2)
	v_mfma_f32_32x32x16_bf16 v[16:31], v[92:95], v[96:99], v[16:31]
	s_waitcnt lgkmcnt(0)
	v_mfma_f32_32x32x16_bf16 v[0:15], v[104:107], v[96:99], v[0:15]
	ds_read_b64_tr_b16 v[92:93], v180 offset:25600
	ds_read_b64_tr_b16 v[94:95], v180 offset:26112
	ds_read_b64_tr_b16 v[96:97], v180 offset:29696
	ds_read_b64_tr_b16 v[98:99], v180 offset:30208
	s_waitcnt lgkmcnt(2)
	v_mfma_f32_32x32x16_bf16 v[16:31], v[92:95], v[100:103], v[16:31]
	s_waitcnt lgkmcnt(0)
	v_mfma_f32_32x32x16_bf16 v[0:15], v[96:99], v[100:103], v[0:15]
	ds_read_b64_tr_b16 v[92:93], v180 offset:26624
	ds_read_b64_tr_b16 v[94:95], v180 offset:27136
	ds_read_b64_tr_b16 v[96:97], v180 offset:30720
	ds_read_b64_tr_b16 v[98:99], v180 offset:31232
	s_waitcnt lgkmcnt(2)
	v_mfma_f32_32x32x16_bf16 v[16:31], v[92:95], v[80:83], v[16:31]
	s_waitcnt lgkmcnt(0)
	v_mfma_f32_32x32x16_bf16 v[0:15], v[96:99], v[80:83], v[0:15]
	ds_read_b64_tr_b16 v[80:81], v180 offset:27648
	ds_read_b64_tr_b16 v[82:83], v180 offset:28160
	ds_read_b64_tr_b16 v[92:93], v180 offset:31744
	ds_read_b64_tr_b16 v[94:95], v180 offset:32256
	s_waitcnt lgkmcnt(2)
	v_mfma_f32_32x32x16_bf16 v[16:31], v[80:83], v[88:91], v[16:31]
	s_waitcnt lgkmcnt(0)
	v_mfma_f32_32x32x16_bf16 v[0:15], v[92:95], v[88:91], v[0:15]
	ds_read_b128 v[80:83], v114 offset:57344
	ds_read_b128 v[182:185], v114 offset:61440
	ds_read_b128 v[186:189], v115 offset:57344
	ds_read_b128 v[190:193], v115 offset:61440
	ds_read_b128 v[200:203], v116 offset:57344
	ds_read_b128 v[204:207], v116 offset:61440
	ds_read_b128 v[208:211], v117 offset:57344
	ds_read_b128 v[212:215], v117 offset:61440
	v_exp_f32_e32 v64, v64
	v_exp_f32_e32 v65, v65
	v_exp_f32_e32 v66, v66
	v_exp_f32_e32 v67, v67
	v_exp_f32_e32 v48, v48
	v_exp_f32_e32 v49, v49
	v_exp_f32_e32 v50, v50
	v_exp_f32_e32 v51, v51
	v_add_f32_e32 v84, v50, v66
	v_add_f32_e32 v85, v51, v67
	v_add_f32_e32 v86, v48, v64
	v_add_f32_e32 v87, v49, v65
	v_cvt_pk_bf16_f32 v64, v64, v65
	v_cvt_pk_bf16_f32 v65, v66, v67
	v_cvt_pk_bf16_f32 v48, v48, v49
	v_cvt_pk_bf16_f32 v49, v50, v51
	s_waitcnt lgkmcnt(7)
	v_mfma_f32_32x32x16_bf16 v[96:111], v[80:83], v[118:121], v[32:47]
	v_exp_f32_e32 v50, v68
	v_exp_f32_e32 v51, v69
	v_exp_f32_e32 v68, v70
	v_exp_f32_e32 v69, v71
	v_add_f32_e32 v70, v50, v86
	v_add_f32_e32 v71, v51, v87
	v_add_f32_e32 v181, v68, v84
	v_add_f32_e32 v228, v69, v85
	v_cvt_pk_bf16_f32 v66, v50, v51
	v_cvt_pk_bf16_f32 v67, v68, v69
	s_waitcnt lgkmcnt(6)
	v_mfma_f32_32x32x16_bf16 v[80:95], v[182:185], v[118:121], v[32:47]
	v_exp_f32_e32 v50, v52
	v_exp_f32_e32 v51, v53
	v_exp_f32_e32 v52, v54
	v_exp_f32_e32 v53, v55
	v_add_f32_e32 v54, v50, v70
	v_add_f32_e32 v55, v51, v71
	v_add_f32_e32 v68, v52, v181
	v_add_f32_e32 v69, v53, v228
	v_cvt_pk_bf16_f32 v50, v50, v51
	v_cvt_pk_bf16_f32 v51, v52, v53
	s_waitcnt lgkmcnt(5)
	v_mfma_f32_32x32x16_bf16 v[96:111], v[186:189], v[122:125], v[96:111]
	v_exp_f32_e32 v52, v72
	v_exp_f32_e32 v53, v73
	v_exp_f32_e32 v70, v74
	v_exp_f32_e32 v71, v75
	v_add_f32_e32 v54, v52, v54
	v_add_f32_e32 v55, v53, v55
	v_add_f32_e32 v72, v70, v68
	v_add_f32_e32 v73, v71, v69
	v_cvt_pk_bf16_f32 v68, v52, v53
	v_cvt_pk_bf16_f32 v69, v70, v71
	s_waitcnt lgkmcnt(4)
	v_mfma_f32_32x32x16_bf16 v[80:95], v[190:193], v[122:125], v[80:95]
	v_exp_f32_e32 v52, v56
	v_exp_f32_e32 v53, v57
	v_exp_f32_e32 v57, v58
	v_exp_f32_e32 v58, v59
	v_add_f32_e32 v54, v52, v54
	v_add_f32_e32 v55, v53, v55
	v_add_f32_e32 v59, v57, v72
	v_add_f32_e32 v70, v58, v73
	v_cvt_pk_bf16_f32 v56, v52, v53
	v_cvt_pk_bf16_f32 v57, v57, v58
	s_waitcnt lgkmcnt(3)
	v_mfma_f32_32x32x16_bf16 v[96:111], v[200:203], v[126:129], v[96:111]
	v_exp_f32_e32 v52, v76
	v_exp_f32_e32 v53, v77
	v_exp_f32_e32 v58, v78
	v_exp_f32_e32 v71, v79
	v_add_f32_e32 v54, v52, v54
	v_add_f32_e32 v55, v53, v55
	v_add_f32_e32 v59, v58, v59
	v_add_f32_e32 v72, v71, v70
	v_cvt_pk_bf16_f32 v70, v52, v53
	v_cvt_pk_bf16_f32 v71, v58, v71
	s_waitcnt lgkmcnt(2)
	v_mfma_f32_32x32x16_bf16 v[80:95], v[204:207], v[126:129], v[80:95]
	v_exp_f32_e32 v58, v60
	v_exp_f32_e32 v60, v61
	v_exp_f32_e32 v61, v62
	v_exp_f32_e32 v62, v63
	v_add_f32_e32 v52, v58, v54
	v_add_f32_e32 v53, v60, v55
	v_add_f32_e32 v54, v61, v59
	v_add_f32_e32 v55, v62, v72
	v_cvt_pk_bf16_f32 v58, v58, v60
	v_cvt_pk_bf16_f32 v59, v61, v62
	s_waitcnt lgkmcnt(1)
	v_mfma_f32_32x32x16_bf16 v[96:111], v[208:211], v[130:133], v[96:111]
	s_waitcnt lgkmcnt(0)
	v_mfma_f32_32x32x16_bf16 v[80:95], v[212:215], v[130:133], v[80:95]
	v_add_f32_e32 v182, v52, v53
	v_add_f32_e32 v183, v54, v55
	v_add_f32_e32 v182, v182, v183
	v_add_f32_e32 v169, v169, v182
	s_waitcnt vmcnt(2)
	s_waitcnt lgkmcnt(0)
	s_barrier
	s_add_i32 m0, s40, 49152
	s_nop 0
	global_load_lds_dwordx4 v174, s[84:85]
	s_add_i32 m0, s41, 8192
	s_nop 0
	global_load_lds_dwordx4 v172, s[82:83]
	s_add_u32 s84, s84, 0x48000
	s_addc_u32 s85, s85, 0
	s_add_u32 s82, s82, 0x48000
	s_addc_u32 s83, s83, 0
	ds_read_b64_tr_b16 v[60:61], v180 offset:32768
	ds_read_b64_tr_b16 v[62:63], v180 offset:33280
	ds_read_b64_tr_b16 v[72:73], v180 offset:36864
	ds_read_b64_tr_b16 v[74:75], v180 offset:37376
	s_waitcnt lgkmcnt(2)
	v_mfma_f32_32x32x16_bf16 v[16:31], v[60:63], v[64:67], v[16:31]
	s_waitcnt lgkmcnt(0)
	v_mfma_f32_32x32x16_bf16 v[0:15], v[72:75], v[64:67], v[0:15]
	ds_read_b64_tr_b16 v[60:61], v180 offset:33792
	ds_read_b64_tr_b16 v[62:63], v180 offset:34304
	ds_read_b64_tr_b16 v[64:65], v180 offset:37888
	ds_read_b64_tr_b16 v[66:67], v180 offset:38400
	s_waitcnt lgkmcnt(2)
	v_mfma_f32_32x32x16_bf16 v[16:31], v[60:63], v[68:71], v[16:31]
	s_waitcnt lgkmcnt(0)
	v_mfma_f32_32x32x16_bf16 v[0:15], v[64:67], v[68:71], v[0:15]
	ds_read_b64_tr_b16 v[60:61], v180 offset:34816
	ds_read_b64_tr_b16 v[62:63], v180 offset:35328
	ds_read_b64_tr_b16 v[64:65], v180 offset:38912
	ds_read_b64_tr_b16 v[66:67], v180 offset:39424
	s_waitcnt lgkmcnt(2)
	v_mfma_f32_32x32x16_bf16 v[16:31], v[60:63], v[48:51], v[16:31]
	s_waitcnt lgkmcnt(0)
	v_mfma_f32_32x32x16_bf16 v[0:15], v[64:67], v[48:51], v[0:15]
	ds_read_b64_tr_b16 v[48:49], v180 offset:35840
	ds_read_b64_tr_b16 v[50:51], v180 offset:36352
	ds_read_b64_tr_b16 v[60:61], v180 offset:39936
	ds_read_b64_tr_b16 v[62:63], v180 offset:40448
	s_waitcnt lgkmcnt(2)
	v_mfma_f32_32x32x16_bf16 v[16:31], v[48:51], v[56:59], v[16:31]
	s_waitcnt lgkmcnt(0)
	v_mfma_f32_32x32x16_bf16 v[0:15], v[60:63], v[56:59], v[0:15]
	ds_read_b128 v[182:185], v114
	ds_read_b128 v[186:189], v114 offset:4096
	ds_read_b128 v[190:193], v115
	ds_read_b128 v[200:203], v115 offset:4096
	ds_read_b128 v[204:207], v116
	ds_read_b128 v[208:211], v116 offset:4096
	ds_read_b128 v[212:215], v117
	ds_read_b128 v[146:149], v117 offset:4096
	v_exp_f32_e32 v64, v96
	v_exp_f32_e32 v65, v97
	v_exp_f32_e32 v66, v98
	v_exp_f32_e32 v67, v99
	v_cvt_pk_bf16_f32 v96, v64, v65
	v_cvt_pk_bf16_f32 v97, v66, v67
	v_exp_f32_e32 v68, v80
	v_exp_f32_e32 v69, v81
	v_exp_f32_e32 v70, v82
	v_exp_f32_e32 v71, v83
	v_cvt_pk_bf16_f32 v80, v68, v69
	v_cvt_pk_bf16_f32 v81, v70, v71
	v_add_f32_e32 v68, v68, v64
	v_add_f32_e32 v69, v69, v65
	v_add_f32_e32 v82, v70, v66
	v_add_f32_e32 v83, v71, v67
	v_exp_f32_e32 v98, v100
	v_exp_f32_e32 v99, v101
	v_exp_f32_e32 v100, v102
	v_exp_f32_e32 v101, v103
	v_add_f32_e32 v102, v98, v68
	v_add_f32_e32 v103, v99, v69
	s_waitcnt lgkmcnt(7)
	v_mfma_f32_32x32x16_bf16 v[64:79], v[182:185], v[118:121], v[32:47]
	v_add_f32_e32 v82, v100, v82
	v_add_f32_e32 v83, v101, v83
	v_cvt_pk_bf16_f32 v98, v98, v99
	v_cvt_pk_bf16_f32 v99, v100, v101
	s_waitcnt lgkmcnt(6)
	v_mfma_f32_32x32x16_bf16 v[48:63], v[186:189], v[118:121], v[32:47]
	v_exp_f32_e32 v84, v84
	v_exp_f32_e32 v85, v85
	v_exp_f32_e32 v86, v86
	v_exp_f32_e32 v87, v87
	v_add_f32_e32 v100, v84, v102
	v_add_f32_e32 v101, v85, v103
	v_add_f32_e32 v102, v86, v82
	v_add_f32_e32 v103, v87, v83
	v_cvt_pk_bf16_f32 v82, v84, v85
	v_cvt_pk_bf16_f32 v83, v86, v87
	s_waitcnt lgkmcnt(5)
	v_mfma_f32_32x32x16_bf16 v[64:79], v[190:193], v[122:125], v[64:79]
	v_exp_f32_e32 v84, v104
	v_exp_f32_e32 v85, v105
	v_exp_f32_e32 v86, v106
	v_exp_f32_e32 v87, v107
	v_add_f32_e32 v104, v84, v100
	v_add_f32_e32 v105, v85, v101
	v_add_f32_e32 v102, v86, v102
	v_add_f32_e32 v103, v87, v103
	v_cvt_pk_bf16_f32 v100, v84, v85
	v_cvt_pk_bf16_f32 v101, v86, v87
	s_waitcnt lgkmcnt(4)
	v_mfma_f32_32x32x16_bf16 v[48:63], v[200:203], v[122:125], v[48:63]
	v_exp_f32_e32 v84, v88
	v_exp_f32_e32 v85, v89
	v_exp_f32_e32 v86, v90
	v_exp_f32_e32 v87, v91
	v_add_f32_e32 v90, v84, v104
	v_add_f32_e32 v91, v85, v105
	v_add_f32_e32 v102, v86, v102
	v_add_f32_e32 v103, v87, v103
	v_cvt_pk_bf16_f32 v88, v84, v85
	v_cvt_pk_bf16_f32 v89, v86, v87
	s_waitcnt lgkmcnt(3)
	v_mfma_f32_32x32x16_bf16 v[64:79], v[204:207], v[126:129], v[64:79]
	v_exp_f32_e32 v84, v108
	v_exp_f32_e32 v85, v109
	v_exp_f32_e32 v86, v110
	v_exp_f32_e32 v87, v111
	v_add_f32_e32 v90, v84, v90
	v_add_f32_e32 v91, v85, v91
	v_add_f32_e32 v104, v86, v102
	v_add_f32_e32 v105, v87, v103
	v_cvt_pk_bf16_f32 v102, v84, v85
	v_cvt_pk_bf16_f32 v103, v86, v87
	s_waitcnt lgkmcnt(2)
	v_mfma_f32_32x32x16_bf16 v[48:63], v[208:211], v[126:129], v[48:63]
	v_exp_f32_e32 v92, v92
	v_exp_f32_e32 v93, v93
	v_exp_f32_e32 v94, v94
	v_exp_f32_e32 v95, v95
	v_add_f32_e32 v84, v92, v90
	v_add_f32_e32 v85, v93, v91
	v_add_f32_e32 v86, v94, v104
	v_add_f32_e32 v87, v95, v105
	v_cvt_pk_bf16_f32 v90, v92, v93
	v_cvt_pk_bf16_f32 v91, v94, v95
	s_waitcnt lgkmcnt(1)
	v_mfma_f32_32x32x16_bf16 v[64:79], v[212:215], v[130:133], v[64:79]
	s_waitcnt lgkmcnt(0)
	v_mfma_f32_32x32x16_bf16 v[48:63], v[146:149], v[130:133], v[48:63]
	v_add_f32_e32 v182, v84, v85
	v_add_f32_e32 v183, v86, v87
	v_add_f32_e32 v182, v182, v183
	v_add_f32_e32 v169, v169, v182
	s_waitcnt vmcnt(2)
	s_waitcnt lgkmcnt(0)
	s_barrier
	s_add_i32 s80, s80, 4
	s_cmp_lt_u32 s80, 60
	s_cbranch_scc1 .Lfa_g1_loop
	s_add_i32 m0, s40, 57344
	s_nop 0
	global_load_lds_dwordx4 v174, s[84:85]
	s_add_i32 m0, s41, 16384
	s_nop 0
	global_load_lds_dwordx4 v172, s[82:83]
	s_add_u32 s84, s84, 0x48000
	s_addc_u32 s85, s85, 0
	s_add_u32 s82, s82, 0x48000
	s_addc_u32 s83, s83, 0
	ds_read_b64_tr_b16 v[92:93], v180 offset:40960
	ds_read_b64_tr_b16 v[94:95], v180 offset:41472
	ds_read_b64_tr_b16 v[104:105], v180 offset:45056
	ds_read_b64_tr_b16 v[106:107], v180 offset:45568
	s_waitcnt lgkmcnt(2)
	v_mfma_f32_32x32x16_bf16 v[16:31], v[92:95], v[96:99], v[16:31]
	s_waitcnt lgkmcnt(0)
	v_mfma_f32_32x32x16_bf16 v[0:15], v[104:107], v[96:99], v[0:15]
	ds_read_b64_tr_b16 v[92:93], v180 offset:41984
	ds_read_b64_tr_b16 v[94:95], v180 offset:42496
	ds_read_b64_tr_b16 v[96:97], v180 offset:46080
	ds_read_b64_tr_b16 v[98:99], v180 offset:46592
	s_waitcnt lgkmcnt(2)
	v_mfma_f32_32x32x16_bf16 v[16:31], v[92:95], v[100:103], v[16:31]
	s_waitcnt lgkmcnt(0)
	v_mfma_f32_32x32x16_bf16 v[0:15], v[96:99], v[100:103], v[0:15]
	ds_read_b64_tr_b16 v[92:93], v180 offset:43008
	ds_read_b64_tr_b16 v[94:95], v180 offset:43520
	ds_read_b64_tr_b16 v[96:97], v180 offset:47104
	ds_read_b64_tr_b16 v[98:99], v180 offset:47616
	s_waitcnt lgkmcnt(2)
	v_mfma_f32_32x32x16_bf16 v[16:31], v[92:95], v[80:83], v[16:31]
	s_waitcnt lgkmcnt(0)
	v_mfma_f32_32x32x16_bf16 v[0:15], v[96:99], v[80:83], v[0:15]
	ds_read_b64_tr_b16 v[80:81], v180 offset:44032
	ds_read_b64_tr_b16 v[82:83], v180 offset:44544
	ds_read_b64_tr_b16 v[92:93], v180 offset:48128
	ds_read_b64_tr_b16 v[94:95], v180 offset:48640
	s_waitcnt lgkmcnt(2)
	v_mfma_f32_32x32x16_bf16 v[16:31], v[80:83], v[88:91], v[16:31]
	s_waitcnt lgkmcnt(0)
	v_mfma_f32_32x32x16_bf16 v[0:15], v[92:95], v[88:91], v[0:15]
	ds_read_b128 v[80:83], v114 offset:8192
	ds_read_b128 v[182:185], v114 offset:12288
	ds_read_b128 v[186:189], v115 offset:8192
	ds_read_b128 v[190:193], v115 offset:12288
	ds_read_b128 v[200:203], v116 offset:8192
	ds_read_b128 v[204:207], v116 offset:12288
	ds_read_b128 v[208:211], v117 offset:8192
	ds_read_b128 v[212:215], v117 offset:12288
	v_exp_f32_e32 v64, v64
	v_exp_f32_e32 v65, v65
	v_exp_f32_e32 v66, v66
	v_exp_f32_e32 v67, v67
	v_exp_f32_e32 v48, v48
	v_exp_f32_e32 v49, v49
	v_exp_f32_e32 v50, v50
	v_exp_f32_e32 v51, v51
	v_add_f32_e32 v84, v50, v66
	v_add_f32_e32 v85, v51, v67
	v_add_f32_e32 v86, v48, v64
	v_add_f32_e32 v87, v49, v65
	v_cvt_pk_bf16_f32 v64, v64, v65
	v_cvt_pk_bf16_f32 v65, v66, v67
	v_cvt_pk_bf16_f32 v48, v48, v49
	v_cvt_pk_bf16_f32 v49, v50, v51
	s_waitcnt lgkmcnt(7)
	v_mfma_f32_32x32x16_bf16 v[96:111], v[80:83], v[118:121], v[32:47]
	v_exp_f32_e32 v50, v68
	v_exp_f32_e32 v51, v69
	v_exp_f32_e32 v68, v70
	v_exp_f32_e32 v69, v71
	v_add_f32_e32 v70, v50, v86
	v_add_f32_e32 v71, v51, v87
	v_add_f32_e32 v181, v68, v84
	v_add_f32_e32 v228, v69, v85
	v_cvt_pk_bf16_f32 v66, v50, v51
	v_cvt_pk_bf16_f32 v67, v68, v69
	s_waitcnt lgkmcnt(6)
	v_mfma_f32_32x32x16_bf16 v[80:95], v[182:185], v[118:121], v[32:47]
	v_exp_f32_e32 v50, v52
	v_exp_f32_e32 v51, v53
	v_exp_f32_e32 v52, v54
	v_exp_f32_e32 v53, v55
	v_add_f32_e32 v54, v50, v70
	v_add_f32_e32 v55, v51, v71
	v_add_f32_e32 v68, v52, v181
	v_add_f32_e32 v69, v53, v228
	v_cvt_pk_bf16_f32 v50, v50, v51
	v_cvt_pk_bf16_f32 v51, v52, v53
	s_waitcnt lgkmcnt(5)
	v_mfma_f32_32x32x16_bf16 v[96:111], v[186:189], v[122:125], v[96:111]
	v_exp_f32_e32 v52, v72
	v_exp_f32_e32 v53, v73
	v_exp_f32_e32 v70, v74
	v_exp_f32_e32 v71, v75
	v_add_f32_e32 v54, v52, v54
	v_add_f32_e32 v55, v53, v55
	v_add_f32_e32 v72, v70, v68
	v_add_f32_e32 v73, v71, v69
	v_cvt_pk_bf16_f32 v68, v52, v53
	v_cvt_pk_bf16_f32 v69, v70, v71
	s_waitcnt lgkmcnt(4)
	v_mfma_f32_32x32x16_bf16 v[80:95], v[190:193], v[122:125], v[80:95]
	v_exp_f32_e32 v52, v56
	v_exp_f32_e32 v53, v57
	v_exp_f32_e32 v57, v58
	v_exp_f32_e32 v58, v59
	v_add_f32_e32 v54, v52, v54
	v_add_f32_e32 v55, v53, v55
	v_add_f32_e32 v59, v57, v72
	v_add_f32_e32 v70, v58, v73
	v_cvt_pk_bf16_f32 v56, v52, v53
	v_cvt_pk_bf16_f32 v57, v57, v58
	s_waitcnt lgkmcnt(3)
	v_mfma_f32_32x32x16_bf16 v[96:111], v[200:203], v[126:129], v[96:111]
	v_exp_f32_e32 v52, v76
	v_exp_f32_e32 v53, v77
	v_exp_f32_e32 v58, v78
	v_exp_f32_e32 v71, v79
	v_add_f32_e32 v54, v52, v54
	v_add_f32_e32 v55, v53, v55
	v_add_f32_e32 v59, v58, v59
	v_add_f32_e32 v72, v71, v70
	v_cvt_pk_bf16_f32 v70, v52, v53
	v_cvt_pk_bf16_f32 v71, v58, v71
	s_waitcnt lgkmcnt(2)
	v_mfma_f32_32x32x16_bf16 v[80:95], v[204:207], v[126:129], v[80:95]
	v_exp_f32_e32 v58, v60
	v_exp_f32_e32 v60, v61
	v_exp_f32_e32 v61, v62
	v_exp_f32_e32 v62, v63
	v_add_f32_e32 v52, v58, v54
	v_add_f32_e32 v53, v60, v55
	v_add_f32_e32 v54, v61, v59
	v_add_f32_e32 v55, v62, v72
	v_cvt_pk_bf16_f32 v58, v58, v60
	v_cvt_pk_bf16_f32 v59, v61, v62
	s_waitcnt lgkmcnt(1)
	v_mfma_f32_32x32x16_bf16 v[96:111], v[208:211], v[130:133], v[96:111]
	s_waitcnt lgkmcnt(0)
	v_mfma_f32_32x32x16_bf16 v[80:95], v[212:215], v[130:133], v[80:95]
	v_add_f32_e32 v182, v52, v53
	v_add_f32_e32 v183, v54, v55
	v_add_f32_e32 v182, v182, v183
	v_add_f32_e32 v169, v169, v182
	s_waitcnt vmcnt(2)
	s_waitcnt lgkmcnt(0)
	s_barrier
	s_add_i32 m0, s41, 24576
	s_nop 0
	global_load_lds_dwordx4 v172, s[82:83]
	s_add_u32 s84, s84, 0x48000
	s_addc_u32 s85, s85, 0
	s_add_u32 s82, s82, 0x48000
	s_addc_u32 s83, s83, 0
	ds_read_b64_tr_b16 v[60:61], v180 offset:16384
	ds_read_b64_tr_b16 v[62:63], v180 offset:16896
	ds_read_b64_tr_b16 v[72:73], v180 offset:20480
	ds_read_b64_tr_b16 v[74:75], v180 offset:20992
	s_waitcnt lgkmcnt(2)
	v_mfma_f32_32x32x16_bf16 v[16:31], v[60:63], v[64:67], v[16:31]
	s_waitcnt lgkmcnt(0)
	v_mfma_f32_32x32x16_bf16 v[0:15], v[72:75], v[64:67], v[0:15]
	ds_read_b64_tr_b16 v[60:61], v180 offset:17408
	ds_read_b64_tr_b16 v[62:63], v180 offset:17920
	ds_read_b64_tr_b16 v[64:65], v180 offset:21504
	ds_read_b64_tr_b16 v[66:67], v180 offset:22016
	s_waitcnt lgkmcnt(2)
	v_mfma_f32_32x32x16_bf16 v[16:31], v[60:63], v[68:71], v[16:31]
	s_waitcnt lgkmcnt(0)
	v_mfma_f32_32x32x16_bf16 v[0:15], v[64:67], v[68:71], v[0:15]
	ds_read_b64_tr_b16 v[60:61], v180 offset:18432
	ds_read_b64_tr_b16 v[62:63], v180 offset:18944
	ds_read_b64_tr_b16 v[64:65], v180 offset:22528
	ds_read_b64_tr_b16 v[66:67], v180 offset:23040
	s_waitcnt lgkmcnt(2)
	v_mfma_f32_32x32x16_bf16 v[16:31], v[60:63], v[48:51], v[16:31]
	s_waitcnt lgkmcnt(0)
	v_mfma_f32_32x32x16_bf16 v[0:15], v[64:67], v[48:51], v[0:15]
	ds_read_b64_tr_b16 v[48:49], v180 offset:19456
	ds_read_b64_tr_b16 v[50:51], v180 offset:19968
	ds_read_b64_tr_b16 v[60:61], v180 offset:23552
	ds_read_b64_tr_b16 v[62:63], v180 offset:24064
	s_waitcnt lgkmcnt(2)
	v_mfma_f32_32x32x16_bf16 v[16:31], v[48:51], v[56:59], v[16:31]
	s_waitcnt lgkmcnt(0)
	v_mfma_f32_32x32x16_bf16 v[0:15], v[60:63], v[56:59], v[0:15]
	ds_read_b128 v[182:185], v114 offset:49152
	ds_read_b128 v[186:189], v114 offset:53248
	ds_read_b128 v[190:193], v115 offset:49152
	ds_read_b128 v[200:203], v115 offset:53248
	ds_read_b128 v[204:207], v116 offset:49152
	ds_read_b128 v[208:211], v116 offset:53248
	ds_read_b128 v[212:215], v117 offset:49152
	ds_read_b128 v[146:149], v117 offset:53248
	v_exp_f32_e32 v64, v96
	v_exp_f32_e32 v65, v97
	v_exp_f32_e32 v66, v98
	v_exp_f32_e32 v67, v99
	v_cvt_pk_bf16_f32 v96, v64, v65
	v_cvt_pk_bf16_f32 v97, v66, v67
	v_exp_f32_e32 v68, v80
	v_exp_f32_e32 v69, v81
	v_exp_f32_e32 v70, v82
	v_exp_f32_e32 v71, v83
	v_cvt_pk_bf16_f32 v80, v68, v69
	v_cvt_pk_bf16_f32 v81, v70, v71
	v_add_f32_e32 v68, v68, v64
	v_add_f32_e32 v69, v69, v65
	v_add_f32_e32 v82, v70, v66
	v_add_f32_e32 v83, v71, v67
	v_exp_f32_e32 v98, v100
	v_exp_f32_e32 v99, v101
	v_exp_f32_e32 v100, v102
	v_exp_f32_e32 v101, v103
	v_add_f32_e32 v102, v98, v68
	v_add_f32_e32 v103, v99, v69
	s_waitcnt lgkmcnt(7)
	v_mfma_f32_32x32x16_bf16 v[64:79], v[182:185], v[118:121], v[32:47]
	v_add_f32_e32 v82, v100, v82
	v_add_f32_e32 v83, v101, v83
	v_cvt_pk_bf16_f32 v98, v98, v99
	v_cvt_pk_bf16_f32 v99, v100, v101
	s_waitcnt lgkmcnt(6)
	v_mfma_f32_32x32x16_bf16 v[48:63], v[186:189], v[118:121], v[32:47]
	v_exp_f32_e32 v84, v84
	v_exp_f32_e32 v85, v85
	v_exp_f32_e32 v86, v86
	v_exp_f32_e32 v87, v87
	v_add_f32_e32 v100, v84, v102
	v_add_f32_e32 v101, v85, v103
	v_add_f32_e32 v102, v86, v82
	v_add_f32_e32 v103, v87, v83
	v_cvt_pk_bf16_f32 v82, v84, v85
	v_cvt_pk_bf16_f32 v83, v86, v87
	s_waitcnt lgkmcnt(5)
	v_mfma_f32_32x32x16_bf16 v[64:79], v[190:193], v[122:125], v[64:79]
	v_exp_f32_e32 v84, v104
	v_exp_f32_e32 v85, v105
	v_exp_f32_e32 v86, v106
	v_exp_f32_e32 v87, v107
	v_add_f32_e32 v104, v84, v100
	v_add_f32_e32 v105, v85, v101
	v_add_f32_e32 v102, v86, v102
	v_add_f32_e32 v103, v87, v103
	v_cvt_pk_bf16_f32 v100, v84, v85
	v_cvt_pk_bf16_f32 v101, v86, v87
	s_waitcnt lgkmcnt(4)
	v_mfma_f32_32x32x16_bf16 v[48:63], v[200:203], v[122:125], v[48:63]
	v_exp_f32_e32 v84, v88
	v_exp_f32_e32 v85, v89
	v_exp_f32_e32 v86, v90
	v_exp_f32_e32 v87, v91
	v_add_f32_e32 v90, v84, v104
	v_add_f32_e32 v91, v85, v105
	v_add_f32_e32 v102, v86, v102
	v_add_f32_e32 v103, v87, v103
	v_cvt_pk_bf16_f32 v88, v84, v85
	v_cvt_pk_bf16_f32 v89, v86, v87
	s_waitcnt lgkmcnt(3)
	v_mfma_f32_32x32x16_bf16 v[64:79], v[204:207], v[126:129], v[64:79]
	v_exp_f32_e32 v84, v108
	v_exp_f32_e32 v85, v109
	v_exp_f32_e32 v86, v110
	v_exp_f32_e32 v87, v111
	v_add_f32_e32 v90, v84, v90
	v_add_f32_e32 v91, v85, v91
	v_add_f32_e32 v104, v86, v102
	v_add_f32_e32 v105, v87, v103
	v_cvt_pk_bf16_f32 v102, v84, v85
	v_cvt_pk_bf16_f32 v103, v86, v87
	s_waitcnt lgkmcnt(2)
	v_mfma_f32_32x32x16_bf16 v[48:63], v[208:211], v[126:129], v[48:63]
	v_exp_f32_e32 v92, v92
	v_exp_f32_e32 v93, v93
	v_exp_f32_e32 v94, v94
	v_exp_f32_e32 v95, v95
	v_add_f32_e32 v84, v92, v90
	v_add_f32_e32 v85, v93, v91
	v_add_f32_e32 v86, v94, v104
	v_add_f32_e32 v87, v95, v105
	v_cvt_pk_bf16_f32 v90, v92, v93
	v_cvt_pk_bf16_f32 v91, v94, v95
	s_waitcnt lgkmcnt(1)
	v_mfma_f32_32x32x16_bf16 v[64:79], v[212:215], v[130:133], v[64:79]
	s_waitcnt lgkmcnt(0)
	v_mfma_f32_32x32x16_bf16 v[48:63], v[146:149], v[130:133], v[48:63]
	v_add_f32_e32 v182, v84, v85
	v_add_f32_e32 v183, v86, v87
	v_add_f32_e32 v182, v182, v183
	v_add_f32_e32 v169, v169, v182
	s_waitcnt vmcnt(1)
	s_waitcnt lgkmcnt(0)
	s_barrier
	s_add_u32 s84, s84, 0x48000
	s_addc_u32 s85, s85, 0
	s_add_u32 s82, s82, 0x48000
	s_addc_u32 s83, s83, 0
	ds_read_b64_tr_b16 v[92:93], v180 offset:24576
	ds_read_b64_tr_b16 v[94:95], v180 offset:25088
	ds_read_b64_tr_b16 v[104:105], v180 offset:28672
	ds_read_b64_tr_b16 v[106:107], v180 offset:29184
	s_waitcnt lgkmcnt(2)
	v_mfma_f32_32x32x16_bf16 v[16:31], v[92:95], v[96:99], v[16:31]
	s_waitcnt lgkmcnt(0)
	v_mfma_f32_32x32x16_bf16 v[0:15], v[104:107], v[96:99], v[0:15]
	ds_read_b64_tr_b16 v[92:93], v180 offset:25600
	ds_read_b64_tr_b16 v[94:95], v180 offset:26112
	ds_read_b64_tr_b16 v[96:97], v180 offset:29696
	ds_read_b64_tr_b16 v[98:99], v180 offset:30208
	s_waitcnt lgkmcnt(2)
	v_mfma_f32_32x32x16_bf16 v[16:31], v[92:95], v[100:103], v[16:31]
	s_waitcnt lgkmcnt(0)
	v_mfma_f32_32x32x16_bf16 v[0:15], v[96:99], v[100:103], v[0:15]
	ds_read_b64_tr_b16 v[92:93], v180 offset:26624
	ds_read_b64_tr_b16 v[94:95], v180 offset:27136
	ds_read_b64_tr_b16 v[96:97], v180 offset:30720
	ds_read_b64_tr_b16 v[98:99], v180 offset:31232
	s_waitcnt lgkmcnt(2)
	v_mfma_f32_32x32x16_bf16 v[16:31], v[92:95], v[80:83], v[16:31]
	s_waitcnt lgkmcnt(0)
	v_mfma_f32_32x32x16_bf16 v[0:15], v[96:99], v[80:83], v[0:15]
	ds_read_b64_tr_b16 v[80:81], v180 offset:27648
	ds_read_b64_tr_b16 v[82:83], v180 offset:28160
	ds_read_b64_tr_b16 v[92:93], v180 offset:31744
	ds_read_b64_tr_b16 v[94:95], v180 offset:32256
	s_waitcnt lgkmcnt(2)
	v_mfma_f32_32x32x16_bf16 v[16:31], v[80:83], v[88:91], v[16:31]
	s_waitcnt lgkmcnt(0)
	v_mfma_f32_32x32x16_bf16 v[0:15], v[92:95], v[88:91], v[0:15]
	ds_read_b128 v[80:83], v114 offset:57344
	ds_read_b128 v[182:185], v114 offset:61440
	ds_read_b128 v[186:189], v115 offset:57344
	ds_read_b128 v[190:193], v115 offset:61440
	ds_read_b128 v[200:203], v116 offset:57344
	ds_read_b128 v[204:207], v116 offset:61440
	ds_read_b128 v[208:211], v117 offset:57344
	ds_read_b128 v[212:215], v117 offset:61440
	v_exp_f32_e32 v64, v64
	v_exp_f32_e32 v65, v65
	v_exp_f32_e32 v66, v66
	v_exp_f32_e32 v67, v67
	v_exp_f32_e32 v48, v48
	v_exp_f32_e32 v49, v49
	v_exp_f32_e32 v50, v50
	v_exp_f32_e32 v51, v51
	v_add_f32_e32 v84, v50, v66
	v_add_f32_e32 v85, v51, v67
	v_add_f32_e32 v86, v48, v64
	v_add_f32_e32 v87, v49, v65
	v_cvt_pk_bf16_f32 v64, v64, v65
	v_cvt_pk_bf16_f32 v65, v66, v67
	v_cvt_pk_bf16_f32 v48, v48, v49
	v_cvt_pk_bf16_f32 v49, v50, v51
	s_waitcnt lgkmcnt(7)
	v_mfma_f32_32x32x16_bf16 v[96:111], v[80:83], v[118:121], v[32:47]
	v_exp_f32_e32 v50, v68
	v_exp_f32_e32 v51, v69
	v_exp_f32_e32 v68, v70
	v_exp_f32_e32 v69, v71
	v_add_f32_e32 v70, v50, v86
	v_add_f32_e32 v71, v51, v87
	v_add_f32_e32 v181, v68, v84
	v_add_f32_e32 v228, v69, v85
	v_cvt_pk_bf16_f32 v66, v50, v51
	v_cvt_pk_bf16_f32 v67, v68, v69
	s_waitcnt lgkmcnt(6)
	v_mfma_f32_32x32x16_bf16 v[80:95], v[182:185], v[118:121], v[32:47]
	v_exp_f32_e32 v50, v52
	v_exp_f32_e32 v51, v53
	v_exp_f32_e32 v52, v54
	v_exp_f32_e32 v53, v55
	v_add_f32_e32 v54, v50, v70
	v_add_f32_e32 v55, v51, v71
	v_add_f32_e32 v68, v52, v181
	v_add_f32_e32 v69, v53, v228
	v_cvt_pk_bf16_f32 v50, v50, v51
	v_cvt_pk_bf16_f32 v51, v52, v53
	s_waitcnt lgkmcnt(5)
	v_mfma_f32_32x32x16_bf16 v[96:111], v[186:189], v[122:125], v[96:111]
	v_exp_f32_e32 v52, v72
	v_exp_f32_e32 v53, v73
	v_exp_f32_e32 v70, v74
	v_exp_f32_e32 v71, v75
	v_add_f32_e32 v54, v52, v54
	v_add_f32_e32 v55, v53, v55
	v_add_f32_e32 v72, v70, v68
	v_add_f32_e32 v73, v71, v69
	v_cvt_pk_bf16_f32 v68, v52, v53
	v_cvt_pk_bf16_f32 v69, v70, v71
	s_waitcnt lgkmcnt(4)
	v_mfma_f32_32x32x16_bf16 v[80:95], v[190:193], v[122:125], v[80:95]
	v_exp_f32_e32 v52, v56
	v_exp_f32_e32 v53, v57
	v_exp_f32_e32 v57, v58
	v_exp_f32_e32 v58, v59
	v_add_f32_e32 v54, v52, v54
	v_add_f32_e32 v55, v53, v55
	v_add_f32_e32 v59, v57, v72
	v_add_f32_e32 v70, v58, v73
	v_cvt_pk_bf16_f32 v56, v52, v53
	v_cvt_pk_bf16_f32 v57, v57, v58
	s_waitcnt lgkmcnt(3)
	v_mfma_f32_32x32x16_bf16 v[96:111], v[200:203], v[126:129], v[96:111]
	v_exp_f32_e32 v52, v76
	v_exp_f32_e32 v53, v77
	v_exp_f32_e32 v58, v78
	v_exp_f32_e32 v71, v79
	v_add_f32_e32 v54, v52, v54
	v_add_f32_e32 v55, v53, v55
	v_add_f32_e32 v59, v58, v59
	v_add_f32_e32 v72, v71, v70
	v_cvt_pk_bf16_f32 v70, v52, v53
	v_cvt_pk_bf16_f32 v71, v58, v71
	s_waitcnt lgkmcnt(2)
	v_mfma_f32_32x32x16_bf16 v[80:95], v[204:207], v[126:129], v[80:95]
	v_exp_f32_e32 v58, v60
	v_exp_f32_e32 v60, v61
	v_exp_f32_e32 v61, v62
	v_exp_f32_e32 v62, v63
	v_add_f32_e32 v52, v58, v54
	v_add_f32_e32 v53, v60, v55
	v_add_f32_e32 v54, v61, v59
	v_add_f32_e32 v55, v62, v72
	v_cvt_pk_bf16_f32 v58, v58, v60
	v_cvt_pk_bf16_f32 v59, v61, v62
	s_waitcnt lgkmcnt(1)
	v_mfma_f32_32x32x16_bf16 v[96:111], v[208:211], v[130:133], v[96:111]
	s_waitcnt lgkmcnt(0)
	v_mfma_f32_32x32x16_bf16 v[80:95], v[212:215], v[130:133], v[80:95]
	v_add_f32_e32 v182, v52, v53
	v_add_f32_e32 v183, v54, v55
	v_add_f32_e32 v182, v182, v183
	v_add_f32_e32 v169, v169, v182
	s_waitcnt vmcnt(0)
	s_waitcnt lgkmcnt(0)
	s_barrier
	s_add_u32 s84, s84, 0x48000
	s_addc_u32 s85, s85, 0
	s_add_u32 s82, s82, 0x48000
	s_addc_u32 s83, s83, 0
	ds_read_b64_tr_b16 v[60:61], v180 offset:32768
	ds_read_b64_tr_b16 v[62:63], v180 offset:33280
	ds_read_b64_tr_b16 v[72:73], v180 offset:36864
	ds_read_b64_tr_b16 v[74:75], v180 offset:37376
	s_waitcnt lgkmcnt(2)
	v_mfma_f32_32x32x16_bf16 v[16:31], v[60:63], v[64:67], v[16:31]
	s_waitcnt lgkmcnt(0)
	v_mfma_f32_32x32x16_bf16 v[0:15], v[72:75], v[64:67], v[0:15]
	ds_read_b64_tr_b16 v[60:61], v180 offset:33792
	ds_read_b64_tr_b16 v[62:63], v180 offset:34304
	ds_read_b64_tr_b16 v[64:65], v180 offset:37888
	ds_read_b64_tr_b16 v[66:67], v180 offset:38400
	s_waitcnt lgkmcnt(2)
	v_mfma_f32_32x32x16_bf16 v[16:31], v[60:63], v[68:71], v[16:31]
	s_waitcnt lgkmcnt(0)
	v_mfma_f32_32x32x16_bf16 v[0:15], v[64:67], v[68:71], v[0:15]
	ds_read_b64_tr_b16 v[60:61], v180 offset:34816
	ds_read_b64_tr_b16 v[62:63], v180 offset:35328
	ds_read_b64_tr_b16 v[64:65], v180 offset:38912
	ds_read_b64_tr_b16 v[66:67], v180 offset:39424
	s_waitcnt lgkmcnt(2)
	v_mfma_f32_32x32x16_bf16 v[16:31], v[60:63], v[48:51], v[16:31]
	s_waitcnt lgkmcnt(0)
	v_mfma_f32_32x32x16_bf16 v[0:15], v[64:67], v[48:51], v[0:15]
	ds_read_b64_tr_b16 v[48:49], v180 offset:35840
	ds_read_b64_tr_b16 v[50:51], v180 offset:36352
	ds_read_b64_tr_b16 v[60:61], v180 offset:39936
	ds_read_b64_tr_b16 v[62:63], v180 offset:40448
	s_waitcnt lgkmcnt(2)
	v_mfma_f32_32x32x16_bf16 v[16:31], v[48:51], v[56:59], v[16:31]
	s_waitcnt lgkmcnt(0)
	v_mfma_f32_32x32x16_bf16 v[0:15], v[60:63], v[56:59], v[0:15]
	v_exp_f32_e32 v64, v96
	v_exp_f32_e32 v65, v97
	v_exp_f32_e32 v66, v98
	v_exp_f32_e32 v67, v99
	v_cvt_pk_bf16_f32 v96, v64, v65
	v_cvt_pk_bf16_f32 v97, v66, v67
	v_exp_f32_e32 v68, v80
	v_exp_f32_e32 v69, v81
	v_exp_f32_e32 v70, v82
	v_exp_f32_e32 v71, v83
	v_cvt_pk_bf16_f32 v80, v68, v69
	v_cvt_pk_bf16_f32 v81, v70, v71
	v_add_f32_e32 v68, v68, v64
	v_add_f32_e32 v69, v69, v65
	v_add_f32_e32 v82, v70, v66
	v_add_f32_e32 v83, v71, v67
	v_exp_f32_e32 v98, v100
	v_exp_f32_e32 v99, v101
	v_exp_f32_e32 v100, v102
	v_exp_f32_e32 v101, v103
	v_add_f32_e32 v102, v98, v68
	v_add_f32_e32 v103, v99, v69
	v_add_f32_e32 v82, v100, v82
	v_add_f32_e32 v83, v101, v83
	v_cvt_pk_bf16_f32 v98, v98, v99
	v_cvt_pk_bf16_f32 v99, v100, v101
	v_exp_f32_e32 v84, v84
	v_exp_f32_e32 v85, v85
	v_exp_f32_e32 v86, v86
	v_exp_f32_e32 v87, v87
	v_add_f32_e32 v100, v84, v102
	v_add_f32_e32 v101, v85, v103
	v_add_f32_e32 v102, v86, v82
	v_add_f32_e32 v103, v87, v83
	v_cvt_pk_bf16_f32 v82, v84, v85
	v_cvt_pk_bf16_f32 v83, v86, v87
	v_exp_f32_e32 v84, v104
	v_exp_f32_e32 v85, v105
	v_exp_f32_e32 v86, v106
	v_exp_f32_e32 v87, v107
	v_add_f32_e32 v104, v84, v100
	v_add_f32_e32 v105, v85, v101
	v_add_f32_e32 v102, v86, v102
	v_add_f32_e32 v103, v87, v103
	v_cvt_pk_bf16_f32 v100, v84, v85
	v_cvt_pk_bf16_f32 v101, v86, v87
	v_exp_f32_e32 v84, v88
	v_exp_f32_e32 v85, v89
	v_exp_f32_e32 v86, v90
	v_exp_f32_e32 v87, v91
	v_add_f32_e32 v90, v84, v104
	v_add_f32_e32 v91, v85, v105
	v_add_f32_e32 v102, v86, v102
	v_add_f32_e32 v103, v87, v103
	v_cvt_pk_bf16_f32 v88, v84, v85
	v_cvt_pk_bf16_f32 v89, v86, v87
	v_exp_f32_e32 v84, v108
	v_exp_f32_e32 v85, v109
	v_exp_f32_e32 v86, v110
	v_exp_f32_e32 v87, v111
	v_add_f32_e32 v90, v84, v90
	v_add_f32_e32 v91, v85, v91
	v_add_f32_e32 v104, v86, v102
	v_add_f32_e32 v105, v87, v103
	v_cvt_pk_bf16_f32 v102, v84, v85
	v_cvt_pk_bf16_f32 v103, v86, v87
	v_exp_f32_e32 v92, v92
	v_exp_f32_e32 v93, v93
	v_exp_f32_e32 v94, v94
	v_exp_f32_e32 v95, v95
	v_add_f32_e32 v84, v92, v90
	v_add_f32_e32 v85, v93, v91
	v_add_f32_e32 v86, v94, v104
	v_add_f32_e32 v87, v95, v105
	v_cvt_pk_bf16_f32 v90, v92, v93
	v_cvt_pk_bf16_f32 v91, v94, v95
	v_add_f32_e32 v182, v84, v85
	v_add_f32_e32 v183, v86, v87
	v_add_f32_e32 v182, v182, v183
	v_add_f32_e32 v169, v169, v182
	s_waitcnt lgkmcnt(0)
	s_barrier
	ds_read_b64_tr_b16 v[92:93], v180 offset:40960
	ds_read_b64_tr_b16 v[94:95], v180 offset:41472
	ds_read_b64_tr_b16 v[104:105], v180 offset:45056
	ds_read_b64_tr_b16 v[106:107], v180 offset:45568
	s_waitcnt lgkmcnt(2)
	v_mfma_f32_32x32x16_bf16 v[16:31], v[92:95], v[96:99], v[16:31]
	s_waitcnt lgkmcnt(0)
	v_mfma_f32_32x32x16_bf16 v[0:15], v[104:107], v[96:99], v[0:15]
	ds_read_b64_tr_b16 v[92:93], v180 offset:41984
	ds_read_b64_tr_b16 v[94:95], v180 offset:42496
	ds_read_b64_tr_b16 v[96:97], v180 offset:46080
	ds_read_b64_tr_b16 v[98:99], v180 offset:46592
	s_waitcnt lgkmcnt(2)
	v_mfma_f32_32x32x16_bf16 v[16:31], v[92:95], v[100:103], v[16:31]
	s_waitcnt lgkmcnt(0)
	v_mfma_f32_32x32x16_bf16 v[0:15], v[96:99], v[100:103], v[0:15]
	ds_read_b64_tr_b16 v[92:93], v180 offset:43008
	ds_read_b64_tr_b16 v[94:95], v180 offset:43520
	ds_read_b64_tr_b16 v[96:97], v180 offset:47104
	ds_read_b64_tr_b16 v[98:99], v180 offset:47616
	s_waitcnt lgkmcnt(2)
	v_mfma_f32_32x32x16_bf16 v[16:31], v[92:95], v[80:83], v[16:31]
	s_waitcnt lgkmcnt(0)
	v_mfma_f32_32x32x16_bf16 v[0:15], v[96:99], v[80:83], v[0:15]
	ds_read_b64_tr_b16 v[80:81], v180 offset:44032
	ds_read_b64_tr_b16 v[82:83], v180 offset:44544
	ds_read_b64_tr_b16 v[92:93], v180 offset:48128
	ds_read_b64_tr_b16 v[94:95], v180 offset:48640
	s_waitcnt lgkmcnt(2)
	v_mfma_f32_32x32x16_bf16 v[16:31], v[80:83], v[88:91], v[16:31]
	s_waitcnt lgkmcnt(0)
	v_mfma_f32_32x32x16_bf16 v[0:15], v[92:95], v[88:91], v[0:15]
	s_branch .LBB0_62
